# attention: batched K reads, Q prefetch+sink hoist (A), scalar adds instead of pk_add, removed per-tile state copies in B attention
# speedup vs baseline: 1.0119x; 1.0119x over previous
; #define LAS3 __attribute__((address_space(3)))
; DI int swz(int row) { return (((row >> 1) & 1) << 2) | ((row >> 2) & 3); }
; template <int MODE>
; DI void attn_seq(const Params& p, int layer, char* smem, const int tid, const int nitems, bf16_t* ob, const int ostride) {
;     ...
;   auto make_lane = [&](const int cs) {
;     AttnLane L;
;     const int rr = r + cs, sw = swz(rr & 15);
;     L.kr0 = rr * 128 + ((0 + h) ^ sw) * 16; L.kr1 = rr * 128 + ((2 + h) ^ sw) * 16; L.kr2 = rr * 128 + ((4 + h) ^ sw) * 16; L.kr3 = rr * 128 + ((6 + h) ^ sw) * 16;
;     const int q = (lane & 15) >> 2, pp = lane & 3, g = (lane >> 4) & 1;
;     const int ra = cs + 4 * h + q, rb = ra + 8;
;     const int lp0 = 2 * g + (pp >> 1), lp1 = 4 + lp0;
;     L.vr00 = ra * 128 + ((lp0 ^ swz(ra & 15)) * 16) + 8 * (pp & 1); L.vr01 = rb * 128 + ((lp0 ^ swz(rb & 15)) * 16) + 8 * (pp & 1);
;     L.vr10 = ra * 128 + ((lp1 ^ swz(ra & 15)) * 16) + 8 * (pp & 1); L.vr11 = rb * 128 + ((lp1 ^ swz(rb & 15)) * 16) + 8 * (pp & 1);
;     return L;
;   };
;     ...
;       } else if (MODE == 1) {
;         const int rrA = d.a0 + 2 * (u - 2), rrB = rrA + 1;
;         const bool inA = (rrA >= wr_lo) && (rrA <= wr_hi), inB = (rrB >= wr_lo) && (rrB <= wr_hi) && (rrB <= d.a1);
;         if (inA || inB) {
;           const int rs_q = clampi(rq - 4, 0, 24);
;           const bool okA = (rrA >= rs_q) && (rrA < rs_q + 8), okB = (rrB >= rs_q) && (rrB < rs_q + 8) && (rrB <= d.a1);
;           LAS3 const float* bA = (okA ? (tab + TAB_HEAD0 + (hq - hq_first) * TAB_HSTR + (rrA - rq + 7) * 31) : (tab + TAB_NEG + 32)) + colbase;
;           LAS3 const float* bB = (okB ? (tab + TAB_HEAD0 + (hq - hq_first) * TAB_HSTR + (rrB - rq + 7) * 31) : (tab + TAB_NEG + 32)) + colbase;
;           attn_chunk<2>(Kb, Kb + 64 * 128, Vb, Vb + 64 * 128, L, q0f, q1f, q2f, q3f, st, st.cinit, h, 0, 0, 0, bA, bB);
;         }
.LBB0_795:
	s_lshl_b32 s0, s87, 15
	s_add_i32 s22, s0, 0
	s_cmp_gt_u32 s21, 1
	s_cselect_b64 s[0:1], -1, 0
	s_and_b64 vcc, s[0:1], exec
	s_cselect_b32 s0, s96, 0
	v_add_u32_e32 v66, s0, v151
	v_lshlrev_b32_e32 v67, 1, v66
	v_and_b32_e32 v67, 4, v67
	v_bfe_u32 v68, v66, 2, 2
	v_lshlrev_b32_e32 v66, 7, v66
	v_bitop3_b32 v69, v67, v152, v68 bitop3:0x36
	v_lshl_or_b32 v183, v69, 4, v66
	v_bitop3_b32 v69, v67, v156, v68 bitop3:0x36
	v_lshl_or_b32 v184, v69, 4, v66
	v_bitop3_b32 v69, v67, v157, v68 bitop3:0x36
	v_bitop3_b32 v67, v67, v158, v68 bitop3:0x36
	v_lshl_or_b32 v185, v69, 4, v66
	v_lshl_or_b32 v186, v67, 4, v66
	v_or_b32_e32 v66, s0, v159
	v_lshlrev_b32_e32 v69, 1, v66
	v_add_u32_e32 v67, 8, v66
	v_lshlrev_b32_e32 v68, 7, v66
	v_and_b32_e32 v69, 4, v69
	v_bfe_u32 v66, v66, 2, 2
	v_bitop3_b32 v70, v69, v160, v66 bitop3:0x36
	v_lshlrev_b32_e32 v70, 4, v70
	v_lshlrev_b32_e32 v71, 1, v67
	v_bitop3_b32 v66, v69, v161, v66 bitop3:0x36
	v_or3_b32 v187, v70, v68, v162
	v_lshlrev_b32_e32 v70, 7, v67
	v_and_b32_e32 v71, 4, v71
	v_bfe_u32 v67, v67, 2, 2
	v_lshlrev_b32_e32 v66, 4, v66
	v_bitop3_b32 v72, v71, v160, v67 bitop3:0x36
	v_or3_b32 v189, v66, v68, v162
	v_bitop3_b32 v66, v71, v161, v67 bitop3:0x36
	v_lshlrev_b32_e32 v72, 4, v72
	v_lshlrev_b32_e32 v66, 4, v66
	v_or3_b32 v188, v72, v70, v162
	v_or3_b32 v190, v66, v70, v162
	s_mov_b64 s[0:1], -1
	s_cbranch_vccz .LBB0_801
	s_lshl_b32 s0, s21, 1
	s_add_i32 s23, s0, s77
	s_add_i32 s24, s23, -8
	s_add_i32 s23, s23, -7
	s_cmp_ge_i32 s24, s2
	s_cselect_b64 s[0:1], -1, 0
	s_cmp_le_i32 s24, s11
	s_cselect_b64 s[6:7], -1, 0
	s_and_b64 s[0:1], s[0:1], s[6:7]
	s_cmp_ge_i32 s23, s2
	s_cselect_b64 s[6:7], -1, 0
	s_cmp_lt_i32 s24, s11
	s_cselect_b64 s[8:9], -1, 0
	s_cmp_lt_i32 s24, s94
	s_cselect_b64 s[88:89], -1, 0
	s_and_b64 s[8:9], s[8:9], s[88:89]
	s_and_b64 s[6:7], s[8:9], s[6:7]
	s_or_b64 s[0:1], s[0:1], s[6:7]
	s_andn2_b64 vcc, exec, s[0:1]
	s_cbranch_vccz .Lm1_compute
	s_mov_b64 s[0:1], 0
	s_mov_b64 s[88:89], 0x1000
	s_and_b64 vcc, exec, s[70:71]
	s_cbranch_vccnz .Lm1_skip_copy
	s_add_i32 s0, s87, 1
	s_cmp_lg_u32 s87, 2
	s_cselect_b32 s87, s0, 0
	s_add_i32 s21, s21, 1
	s_branch .LBB0_777
.Lm1_skip_copy:
	v_mov_b64_e32 v[114:115], v[48:49]
	v_mov_b64_e32 v[80:81], v[32:33]
	v_mov_b64_e32 v[96:97], v[64:65]
	v_mov_b32_e32 v98, v181
	v_mov_b32_e32 v191, v182
	v_mov_b64_e32 v[112:113], v[46:47]
	v_mov_b64_e32 v[110:111], v[44:45]
	v_mov_b64_e32 v[108:109], v[42:43]
	v_mov_b64_e32 v[106:107], v[40:41]
	v_mov_b64_e32 v[104:105], v[38:39]
	v_mov_b64_e32 v[102:103], v[36:37]
	v_mov_b64_e32 v[100:101], v[34:35]
	v_mov_b64_e32 v[78:79], v[30:31]
	v_mov_b64_e32 v[76:77], v[28:29]
	v_mov_b64_e32 v[74:75], v[26:27]
	v_mov_b64_e32 v[72:73], v[24:25]
	v_mov_b64_e32 v[70:71], v[22:23]
	v_mov_b64_e32 v[68:69], v[20:21]
	v_mov_b64_e32 v[66:67], v[18:19]
	v_mov_b64_e32 v[94:95], v[62:63]
	v_mov_b64_e32 v[92:93], v[60:61]
	v_mov_b64_e32 v[90:91], v[58:59]
	v_mov_b64_e32 v[88:89], v[56:57]
	v_mov_b64_e32 v[86:87], v[54:55]
	v_mov_b64_e32 v[84:85], v[52:53]
	v_mov_b64_e32 v[82:83], v[50:51]
	s_branch .LBB0_800
.Lm1_compute:
	v_add_u32_e32 v66, s22, v183
	ds_read_b128 v[82:85], v66
	ds_read_b128 v[100:103], v66 offset:8192
	v_add_u32_e32 v86, s22, v184
	v_add_u32_e32 v87, s22, v185
	v_cmp_ge_i32_e64 s[6:7], s23, v135
	v_cmp_lt_i32_e64 s[8:9], s23, v137
	s_and_b64 s[6:7], s[6:7], s[8:9]
	s_movk_i32 s8, 0x7c
	v_cmp_ge_i32_e32 vcc, s24, v135
	s_waitcnt lgkmcnt(0)
	v_mfma_f32_32x32x16_bf16 v[66:81], v[82:85], v[128:131], v[34:49]
	ds_read_b128 v[82:85], v86
	ds_read_b128 v[104:107], v86 offset:8192
	v_add_u32_e32 v86, s22, v186
	v_cmp_lt_i32_e64 s[0:1], s24, v137
	v_readlane_b32 s9, v255, 23
	s_and_b64 vcc, vcc, s[0:1]
	ds_read_b128 v[108:111], v87 offset:8192
	s_waitcnt lgkmcnt(0)
	v_mfma_f32_32x32x16_bf16 v[66:81], v[82:85], v[124:127], v[66:81]
	ds_read_b128 v[82:85], v87
	s_waitcnt lgkmcnt(0)
	v_mfma_f32_32x32x16_bf16 v[66:81], v[82:85], v[120:123], v[66:81]
	ds_read_b128 v[82:85], v86
	ds_read_b128 v[112:115], v86 offset:8192
	s_waitcnt lgkmcnt(0)
	v_mfma_f32_32x32x16_bf16 v[66:81], v[82:85], v[116:119], v[66:81]
	v_sub_u32_e32 v82, s24, v99
	v_mul_lo_u32 v98, v82, s8
	v_add_u32_e32 v98, s20, v98
	v_add_u32_e32 v98, 0x364, v98
	v_mfma_f32_32x32x16_bf16 v[82:97], v[100:103], v[128:131], v[34:49]
	v_sub_u32_e32 v101, s23, v99
	v_mul_lo_u32 v101, v101, s8
	v_mov_b32_e32 v100, s9
	v_add_u32_e32 v101, s20, v101
	v_cndmask_b32_e32 v98, v100, v98, vcc
	v_add_u32_e32 v101, 0x364, v101
	s_and_b64 vcc, s[6:7], s[88:89]
	v_mfma_f32_32x32x16_bf16 v[82:97], v[104:107], v[124:127], v[82:97]
	v_add_u32_e32 v98, v98, v168
	v_cndmask_b32_e32 v100, v100, v101, vcc
	v_add_u32_e32 v191, v100, v168
	ds_read2_b32 v[100:101], v98 offset0:15 offset1:16
	ds_read2_b32 v[102:103], v98 offset0:17 offset1:18
	ds_read2_b32 v[104:105], v98 offset0:23 offset1:24
	ds_read2_b32 v[106:107], v98 offset0:25 offset1:26
	s_waitcnt lgkmcnt(0)
	v_add_f32_e32 v102, v68, v102
	v_mfma_f32_32x32x16_bf16 v[82:97], v[108:111], v[120:123], v[82:97]
	ds_read2_b32 v[108:109], v191 offset0:15 offset1:16
	ds_read2_b32 v[110:111], v191 offset0:17 offset1:18
	ds_read2_b32 v[192:193], v191 offset0:23 offset1:24
	ds_read2_b32 v[194:195], v191 offset0:25 offset1:26
	v_add_f32_e32 v100, v66, v100
	v_add_f32_e32 v101, v67, v101
	v_add_f32_e32 v103, v69, v103
	v_add_f32_e32 v104, v70, v104
	v_add_f32_e32 v105, v71, v105
	v_add_f32_e32 v106, v72, v106
	v_mfma_f32_32x32x16_bf16 v[82:97], v[112:115], v[116:119], v[82:97]
	v_add_f32_e32 v107, v73, v107
	v_exp_f32_e32 v226, v100
	v_exp_f32_e32 v228, v101
	v_exp_f32_e32 v230, v102
	v_exp_f32_e32 v232, v103
	v_exp_f32_e32 v234, v104
	v_exp_f32_e32 v236, v105
	s_waitcnt lgkmcnt(0)
; DI void pv_tile(LAS3 const char* vb, const AttnLane& L, const f32x16& pr, f32x16& o0, f32x16& o1) {
;   u32x4 w0, w1;
;   w0[0] = pk2(pr[0], pr[1]); w0[1] = pk2(pr[2], pr[3]); w0[2] = pk2(pr[4], pr[5]); w0[3] = pk2(pr[6], pr[7]);
;   w1[0] = pk2(pr[8], pr[9]); w1[1] = pk2(pr[10], pr[11]); w1[2] = pk2(pr[12], pr[13]); w1[3] = pk2(pr[14], pr[15]);
;   const bf16x8 pf0 = __builtin_bit_cast(bf16x8, w0), pf1 = __builtin_bit_cast(bf16x8, w1);
;   o0 = __builtin_amdgcn_mfma_f32_32x32x16_bf16(tr_pair(vb + L.vr00, vb + L.vr01), pf0, o0, 0, 0, 0);
;   o1 = __builtin_amdgcn_mfma_f32_32x32x16_bf16(tr_pair(vb + L.vr10, vb + L.vr11), pf0, o1, 0, 0, 0);
; template <int MK> ...
;     ...
;   if (MK == 2) {
; #pragma unroll
;     for (int v = 0; v < 16; ++v) { s0[v] += b0[(v & 3) + 8 * (v >> 2)]; s1[v] += b1[(v & 3) + 8 * (v >> 2)]; }
;   }
;   if (MK == 1 && kb1 != 0x7fffffff) {
;     const int lo = max(0, sq - 128), hi = min(2047, sq + 128);
;     const int L0 = lo - kb0 - 4 * h, H0 = hi - kb0 - 4 * h, L1 = lo - kb1 - 4 * h, H1 = hi - kb1 - 4 * h;
; #pragma unroll
;     for (int v = 0; v < 16; ++v) {
;       const int cv = (v & 3) + 8 * (v >> 2);
;       s0[v] = (cv >= L0 && cv <= H0) ? s0[v] : -1e30f;
;       s1[v] = (cv >= L1 && cv <= H1) ? s1[v] : -1e30f;
;     }
;   }
; #pragma unroll
;   for (int v = 0; v < 16; ++v) s0[v] = __builtin_amdgcn_exp2f(s0[v]);
;   const float a0 = (s0[0] + s0[1]) + (s0[2] + s0[3]), a1 = (s0[4] + s0[5]) + (s0[6] + s0[7]);
;   const float a2 = (s0[8] + s0[9]) + (s0[10] + s0[11]), a3 = (s0[12] + s0[13]) + (s0[14] + s0[15]);
;   pv_tile(v0, L, s0, st.o0, st.o1);
; #pragma unroll
;   for (int v = 0; v < 16; ++v) s1[v] = __builtin_amdgcn_exp2f(s1[v]);
;   const float a4 = (s1[0] + s1[1]) + (s1[2] + s1[3]), a5 = (s1[4] + s1[5]) + (s1[6] + s1[7]);
;   const float a6 = (s1[8] + s1[9]) + (s1[10] + s1[11]), a7 = (s1[12] + s1[13]) + (s1[14] + s1[15]);
;   pv_tile(v1, L, s1, st.o0, st.o1);
;   const float sum = ((a0 + a1) + (a2 + a3)) + ((a4 + a5) + (a6 + a7));
;   st.l += sum;
;   const float tot = sum + __shfl_xor(sum, 32);
;   if (__builtin_amdgcn_ballot_w64(tot > 256.f) != 0) {
;     const float delta = fmaxf(__builtin_amdgcn_logf(tot), 0.f);
;     const float alpha = __builtin_amdgcn_exp2f(-delta);
;     st.m += delta; st.l *= alpha;
; #pragma unroll
;     for (int v = 0; v < 16; ++v) { st.cinit[v] -= delta; st.o0[v] *= alpha; st.o1[v] *= alpha; }
;   }
	s_nop 3
	v_add_f32_e32 v108, v82, v108
	v_add_f32_e32 v109, v83, v109
	ds_read2_b32 v[66:67], v98 offset0:31 offset1:32
	ds_read2_b32 v[68:69], v191 offset0:31 offset1:32
	ds_read2_b32 v[70:71], v98 offset0:33 offset1:34
	ds_read2_b32 v[72:73], v98 offset0:39 offset1:40
	ds_read2_b32 v[82:83], v98 offset0:41 offset1:42
	v_add_f32_e32 v110, v84, v110
	v_add_f32_e32 v111, v85, v111
	v_add_f32_e32 v196, v86, v192
	v_add_f32_e32 v213, v87, v193
	v_add_f32_e32 v221, v88, v194
	v_add_f32_e32 v225, v89, v195
	ds_read2_b32 v[84:85], v191 offset0:33 offset1:34
	ds_read2_b32 v[86:87], v191 offset0:39 offset1:40
	ds_read2_b32 v[88:89], v191 offset0:41 offset1:42
	s_waitcnt lgkmcnt(0)
	v_add_f32_e32 v191, v91, v69
	v_add_f32_e32 v69, v77, v71
	v_add_f32_e32 v71, v79, v73
	v_add_f32_e32 v98, v90, v68
	v_add_f32_e32 v68, v76, v70
	v_exp_f32_e32 v252, v71
	v_add_u32_e32 v71, s22, v188
	v_exp_f32_e32 v246, v68
	v_exp_f32_e32 v248, v69
	s_nop 0
	ds_read_b64_tr_b16 v[68:69], v71 offset:16384
	v_add_f32_e32 v70, v78, v72
	v_add_f32_e32 v72, v80, v82
	v_add_f32_e32 v73, v81, v83
	v_exp_f32_e32 v238, v106
	v_exp_f32_e32 v240, v107
	v_exp_f32_e32 v220, v72
	v_add_u32_e32 v72, s22, v189
	v_exp_f32_e32 v212, v73
	v_add_u32_e32 v73, s22, v190
	ds_read_b64_tr_b16 v[100:101], v72 offset:16384
	ds_read_b64_tr_b16 v[102:103], v73 offset:16384
	v_add_f32_e32 v66, v74, v66
	v_add_f32_e32 v67, v75, v67
	v_exp_f32_e32 v250, v70
	v_add_u32_e32 v70, s22, v187
	v_cvt_pk_bf16_f32 v192, v226, v228
	v_cvt_pk_bf16_f32 v193, v230, v232
	v_cvt_pk_bf16_f32 v194, v234, v236
	v_cvt_pk_bf16_f32 v195, v238, v240
	v_add_f32_e32 v247, v92, v84
	v_add_f32_e32 v249, v93, v85
	v_add_f32_e32 v251, v94, v86
	v_add_f32_e32 v253, v95, v87
	v_add_f32_e32 v215, v96, v88
	v_add_f32_e32 v219, v97, v89
	v_exp_f32_e32 v242, v66
	v_exp_f32_e32 v244, v67
	v_exp_f32_e32 v227, v108
	v_exp_f32_e32 v229, v109
	v_exp_f32_e32 v231, v110
	v_exp_f32_e32 v233, v111
	ds_read_b64_tr_b16 v[66:67], v70 offset:16384
	ds_read_b64_tr_b16 v[104:105], v70 offset:18432
	ds_read_b64_tr_b16 v[108:109], v70 offset:24576
	ds_read_b64_tr_b16 v[112:113], v70 offset:26624
	ds_read_b64_tr_b16 v[106:107], v71 offset:18432
	ds_read_b64_tr_b16 v[110:111], v71 offset:24576
	ds_read_b64_tr_b16 v[114:115], v71 offset:26624
	s_waitcnt lgkmcnt(6)
	v_mfma_f32_32x32x16_bf16 v[50:65], v[66:69], v[192:195], v[50:65]
	v_exp_f32_e32 v235, v196
	ds_read_b64_tr_b16 v[196:197], v72 offset:18432
	ds_read_b64_tr_b16 v[200:201], v72 offset:24576
	ds_read_b64_tr_b16 v[204:205], v72 offset:26624
	ds_read_b64_tr_b16 v[198:199], v73 offset:18432
	ds_read_b64_tr_b16 v[202:203], v73 offset:24576
	ds_read_b64_tr_b16 v[206:207], v73 offset:26624
	v_exp_f32_e32 v237, v213
	v_exp_f32_e32 v239, v221
	v_exp_f32_e32 v241, v225
	v_exp_f32_e32 v243, v98
	v_exp_f32_e32 v245, v191
	v_mfma_f32_32x32x16_bf16 v[18:33], v[100:103], v[192:195], v[18:33]
	v_cvt_pk_bf16_f32 v100, v242, v244
	v_cvt_pk_bf16_f32 v101, v246, v248
	v_cvt_pk_bf16_f32 v102, v250, v252
	v_cvt_pk_bf16_f32 v103, v220, v212
	v_exp_f32_e32 v247, v247
	v_exp_f32_e32 v249, v249
	v_exp_f32_e32 v251, v251
	s_waitcnt lgkmcnt(8)
	v_mfma_f32_32x32x16_bf16 v[50:65], v[104:107], v[100:103], v[50:65]
	v_exp_f32_e32 v253, v253
	v_exp_f32_e32 v221, v215
	v_exp_f32_e32 v213, v219
	v_add_f32_e32 v104, v226, v228
	v_add_f32_e32 v105, v227, v229
	v_add_f32_e32 v106, v230, v232
	v_add_f32_e32 v107, v231, v233
	v_xor_b32_e32 v98, 32, v214
	v_add_f32_e32 v104, v104, v106
	v_add_f32_e32 v105, v105, v107
	s_waitcnt lgkmcnt(2)
	v_mfma_f32_32x32x16_bf16 v[18:33], v[196:199], v[100:103], v[18:33]
	v_cvt_pk_bf16_f32 v100, v227, v229
	v_cvt_pk_bf16_f32 v101, v231, v233
	v_cvt_pk_bf16_f32 v102, v235, v237
	v_cvt_pk_bf16_f32 v103, v239, v241
	v_add_f32_e64 v106, v234, v236
	v_add_f32_e64 v107, v235, v237
	v_mfma_f32_32x32x16_bf16 v[50:65], v[108:111], v[100:103], v[50:65]
	v_add_f32_e64 v108, v238, v240
	v_add_f32_e64 v109, v239, v241
	v_add_f32_e64 v110, v246, v248
	v_add_f32_e64 v111, v247, v249
	v_add_f32_e64 v106, v106, v108
	v_add_f32_e64 v107, v107, v109
	v_add_f32_e32 v108, v242, v244
	v_add_f32_e32 v109, v243, v245
	v_add_f32_e32 v104, v104, v106
	v_add_f32_e32 v105, v105, v107
	v_add_f32_e32 v108, v108, v110
	v_add_f32_e32 v109, v109, v111
	s_waitcnt lgkmcnt(1)
	v_mfma_f32_32x32x16_bf16 v[18:33], v[200:203], v[100:103], v[18:33]
	v_add_f32_e64 v100, v250, v252
	v_add_f32_e64 v101, v251, v253
	v_add_f32_e64 v102, v220, v212
	v_add_f32_e64 v103, v221, v213
	v_add_f32_e64 v110, v100, v102
	v_add_f32_e64 v111, v101, v103
	v_cvt_pk_bf16_f32 v100, v243, v245
	v_add_f32_e32 v106, v108, v110
	v_add_f32_e32 v107, v109, v111
	v_cvt_pk_bf16_f32 v101, v247, v249
	v_add_f32_e32 v104, v104, v106
	v_add_f32_e32 v105, v105, v107
	v_cvt_pk_bf16_f32 v102, v251, v253
	v_add_f32_e32 v104, v104, v105
	v_and_b32_e32 v105, 64, v214
	v_add_u32_e32 v105, 64, v105
	v_cmp_lt_i32_e32 vcc, v98, v105
	v_cvt_pk_bf16_f32 v103, v221, v213
	s_nop 0
	v_cndmask_b32_e32 v98, v214, v98, vcc
	v_mfma_f32_32x32x16_bf16 v[50:65], v[112:115], v[100:103], v[50:65]
	v_lshlrev_b32_e32 v98, 2, v98
	ds_bpermute_b32 v105, v98, v104
	v_add_f32_e32 v181, v181, v104
	s_waitcnt lgkmcnt(1)
	v_mfma_f32_32x32x16_bf16 v[18:33], v[204:207], v[100:103], v[18:33]
	s_waitcnt lgkmcnt(0)
	v_add_f32_e32 v100, v104, v105
	v_cmp_lt_f32_e32 vcc, s68, v100
	s_cbranch_vccz .Lm1_cdone
	v_log_f32_e32 v100, v100
	s_nop 0
	v_max_f32_e32 v100, 0, v100
	v_exp_f32_e64 v192, -v100
	v_add_f32_e32 v182, v182, v100
	v_sub_f32_e32 v49, v49, v100
	v_sub_f32_e32 v48, v48, v100
	v_sub_f32_e32 v47, v47, v100
	v_sub_f32_e32 v46, v46, v100
	v_sub_f32_e32 v45, v45, v100
	v_mul_f32_e32 v181, v181, v192
	v_sub_f32_e32 v44, v44, v100
	v_sub_f32_e32 v43, v43, v100
	v_sub_f32_e32 v42, v42, v100
	v_sub_f32_e32 v41, v41, v100
	v_sub_f32_e32 v40, v40, v100
	v_sub_f32_e32 v39, v39, v100
	v_sub_f32_e32 v38, v38, v100
	v_sub_f32_e32 v37, v37, v100
	v_sub_f32_e32 v36, v36, v100
	v_sub_f32_e32 v35, v35, v100
	v_sub_f32_e32 v34, v34, v100
	v_pk_mul_f32 v[64:65], v[64:65], v[192:193] op_sel_hi:[1,0]
	v_pk_mul_f32 v[62:63], v[62:63], v[192:193] op_sel_hi:[1,0]
	v_pk_mul_f32 v[60:61], v[60:61], v[192:193] op_sel_hi:[1,0]
	v_pk_mul_f32 v[58:59], v[58:59], v[192:193] op_sel_hi:[1,0]
	v_pk_mul_f32 v[56:57], v[56:57], v[192:193] op_sel_hi:[1,0]
	v_pk_mul_f32 v[54:55], v[54:55], v[192:193] op_sel_hi:[1,0]
	v_pk_mul_f32 v[52:53], v[52:53], v[192:193] op_sel_hi:[1,0]
	v_pk_mul_f32 v[50:51], v[50:51], v[192:193] op_sel_hi:[1,0]
	v_pk_mul_f32 v[32:33], v[32:33], v[192:193] op_sel_hi:[1,0]
	v_pk_mul_f32 v[30:31], v[30:31], v[192:193] op_sel_hi:[1,0]
	v_pk_mul_f32 v[28:29], v[28:29], v[192:193] op_sel_hi:[1,0]
	v_pk_mul_f32 v[26:27], v[26:27], v[192:193] op_sel_hi:[1,0]
	v_pk_mul_f32 v[24:25], v[24:25], v[192:193] op_sel_hi:[1,0]
	v_pk_mul_f32 v[22:23], v[22:23], v[192:193] op_sel_hi:[1,0]
	v_pk_mul_f32 v[20:21], v[20:21], v[192:193] op_sel_hi:[1,0]
	v_pk_mul_f32 v[18:19], v[18:19], v[192:193] op_sel_hi:[1,0]
; #define LAS3 __attribute__((address_space(3)))
; template <int MODE>
; DI void attn_seq(const Params& p, int layer, char* smem, const int tid, const int nitems, bf16_t* ob, const int ostride) {
;     ...
;     for (int u = 0; u < d.nt; ++u) {
;       if (gvalid || !(k == nit - 1 && u == d.nt - 1)) asm volatile("s_waitcnt vmcnt(4)" ::: "memory");
;       else asm volatile("s_waitcnt vmcnt(0)" ::: "memory");
;       __builtin_amdgcn_s_barrier();
;       asm volatile("" ::: "memory");
;       if (gvalid) gen_issue();
;       LAS3 const char* Kb = lds + sc * ATT_STAGE;
;       LAS3 const char* Vb = Kb + 16384;
;       slast = sc;
;       sc = (sc == ATT_NST - 1) ? 0 : sc + 1;
.Lm1_cdone:
	s_mov_b64 s[88:89], 0x1000
	s_and_b64 vcc, exec, s[70:71]
	s_cbranch_vccnz .Lm1_clast
	s_add_i32 s0, s87, 1
	s_cmp_lg_u32 s87, 2
	s_cselect_b32 s87, s0, 0
	s_add_i32 s21, s21, 1
	s_branch .LBB0_777
.Lm1_clast:
	s_nop 7
	s_nop 3
	v_mov_b64_e32 v[114:115], v[48:49]
	v_mov_b64_e32 v[80:81], v[32:33]
	v_mov_b64_e32 v[96:97], v[64:65]
	v_mov_b32_e32 v98, v181
	v_mov_b32_e32 v191, v182
	v_mov_b64_e32 v[112:113], v[46:47]
	v_mov_b64_e32 v[110:111], v[44:45]
	v_mov_b64_e32 v[108:109], v[42:43]
	v_mov_b64_e32 v[106:107], v[40:41]
	v_mov_b64_e32 v[104:105], v[38:39]
	v_mov_b64_e32 v[102:103], v[36:37]
	v_mov_b64_e32 v[100:101], v[34:35]
	v_mov_b64_e32 v[78:79], v[30:31]
	v_mov_b64_e32 v[76:77], v[28:29]
	v_mov_b64_e32 v[74:75], v[26:27]
	v_mov_b64_e32 v[72:73], v[24:25]
	v_mov_b64_e32 v[70:71], v[22:23]
	v_mov_b64_e32 v[68:69], v[20:21]
	v_mov_b64_e32 v[66:67], v[18:19]
	v_mov_b64_e32 v[94:95], v[62:63]
	v_mov_b64_e32 v[92:93], v[60:61]
	v_mov_b64_e32 v[90:91], v[58:59]
	v_mov_b64_e32 v[88:89], v[56:57]
	v_mov_b64_e32 v[86:87], v[54:55]
	v_mov_b64_e32 v[84:85], v[52:53]
	v_mov_b64_e32 v[82:83], v[50:51]

; template <int MK> ...
;   f32x16 s0 = qk_tile(k0, L, q0, q1, q2, q3, init);
;   f32x16 s1 = qk_tile(k1, L, q0, q1, q2, q3, init);
;   if (MK == 2) {
; #pragma unroll
;     for (int v = 0; v < 16; ++v) { s0[v] += b0[(v & 3) + 8 * (v >> 2)]; s1[v] += b1[(v & 3) + 8 * (v >> 2)]; }
;   }
;   if (MK == 1 && kb1 != 0x7fffffff) {
;     const int lo = max(0, sq - 128), hi = min(2047, sq + 128);
;     const int L0 = lo - kb0 - 4 * h, H0 = hi - kb0 - 4 * h, L1 = lo - kb1 - 4 * h, H1 = hi - kb1 - 4 * h;
; #pragma unroll
;     for (int v = 0; v < 16; ++v) {
;       const int cv = (v & 3) + 8 * (v >> 2);
;       s0[v] = (cv >= L0 && cv <= H0) ? s0[v] : -1e30f;
;       s1[v] = (cv >= L1 && cv <= H1) ? s1[v] : -1e30f;
;     }
;   }
; #pragma unroll
;   for (int v = 0; v < 16; ++v) s0[v] = __builtin_amdgcn_exp2f(s0[v]);
;   const float a0 = (s0[0] + s0[1]) + (s0[2] + s0[3]), a1 = (s0[4] + s0[5]) + (s0[6] + s0[7]);
;   const float a2 = (s0[8] + s0[9]) + (s0[10] + s0[11]), a3 = (s0[12] + s0[13]) + (s0[14] + s0[15]);
;   pv_tile(v0, L, s0, st.o0, st.o1);
; #pragma unroll
;   for (int v = 0; v < 16; ++v) s1[v] = __builtin_amdgcn_exp2f(s1[v]);
;   const float a4 = (s1[0] + s1[1]) + (s1[2] + s1[3]), a5 = (s1[4] + s1[5]) + (s1[6] + s1[7]);
;   const float a6 = (s1[8] + s1[9]) + (s1[10] + s1[11]), a7 = (s1[12] + s1[13]) + (s1[14] + s1[15]);
;   pv_tile(v1, L, s1, st.o0, st.o1);
;   const float sum = ((a0 + a1) + (a2 + a3)) + ((a4 + a5) + (a6 + a7));
;   st.l += sum;
;   const float tot = sum + __shfl_xor(sum, 32);
.LBB0_804:
	s_add_i32 s6, s22, s6
	v_add_u32_e32 v82, s6, v183
	ds_read_b128 v[100:103], v82
	ds_read_b128 v[104:107], v82 offset:4096
	v_xor_b32_e32 v66, 0x80000000, v182
	v_mov_b32_e32 v67, v66
	v_mov_b32_e32 v68, v66
	v_mov_b32_e32 v69, v66
	v_mov_b32_e32 v70, v66
	v_mov_b32_e32 v71, v66
	v_mov_b32_e32 v72, v66
	v_mov_b32_e32 v73, v66
	v_mov_b32_e32 v74, v66
	v_mov_b32_e32 v75, v66
	v_mov_b32_e32 v76, v66
	v_mov_b32_e32 v77, v66
	v_mov_b32_e32 v78, v66
	v_mov_b32_e32 v79, v66
	v_mov_b32_e32 v80, v66
	v_mov_b32_e32 v81, v66
	v_add_u32_e32 v108, s6, v184
	v_add_u32_e32 v112, s6, v185
	s_waitcnt lgkmcnt(0)
	v_mfma_f32_32x32x16_bf16 v[82:97], v[100:103], v[128:131], v[66:81]
	ds_read_b128 v[100:103], v108
	ds_read_b128 v[108:111], v108 offset:4096
	v_add_u32_e32 v191, s6, v186
	s_waitcnt lgkmcnt(0)
	v_mfma_f32_32x32x16_bf16 v[82:97], v[100:103], v[124:127], v[82:97]
	ds_read_b128 v[100:103], v112
	ds_read_b128 v[112:115], v112 offset:4096
	s_waitcnt lgkmcnt(0)
	v_mfma_f32_32x32x16_bf16 v[82:97], v[100:103], v[120:123], v[82:97]
	v_mfma_f32_32x32x16_bf16 v[66:81], v[104:107], v[128:131], v[66:81]
	ds_read_b128 v[100:103], v191
	ds_read_b128 v[104:107], v191 offset:4096
	s_waitcnt lgkmcnt(0)
	v_mfma_f32_32x32x16_bf16 v[82:97], v[100:103], v[116:119], v[82:97]
	v_add_u32_e32 v102, s6, v188
	v_mfma_f32_32x32x16_bf16 v[66:81], v[108:111], v[124:127], v[66:81]
	s_nop 9
	v_exp_f32_e32 v196, v84
	v_exp_f32_e32 v198, v85
	s_nop 0
	ds_read_b64_tr_b16 v[84:85], v102 offset:16384
	v_add_u32_e32 v110, s6, v189
	v_exp_f32_e32 v192, v82
	v_exp_f32_e32 v194, v83
	v_exp_f32_e32 v200, v86
	v_mfma_f32_32x32x16_bf16 v[66:81], v[112:115], v[120:123], v[66:81]
	v_exp_f32_e32 v202, v87
	v_exp_f32_e32 v204, v88
	v_exp_f32_e32 v206, v89
	v_add_u32_e32 v114, s6, v190
	ds_read_b64_tr_b16 v[86:87], v110 offset:16384
	ds_read_b64_tr_b16 v[88:89], v114 offset:16384
	v_exp_f32_e32 v230, v92
	v_add_u32_e32 v92, s6, v187
	v_mfma_f32_32x32x16_bf16 v[66:81], v[104:107], v[116:119], v[66:81]
	v_cvt_pk_bf16_f32 v104, v192, v194
	v_cvt_pk_bf16_f32 v105, v196, v198
	v_cvt_pk_bf16_f32 v106, v200, v202
	v_cvt_pk_bf16_f32 v107, v204, v206
	v_exp_f32_e32 v226, v90
	v_exp_f32_e32 v228, v91
	v_exp_f32_e32 v232, v93
	v_exp_f32_e32 v234, v94
	v_exp_f32_e32 v236, v95
	v_exp_f32_e32 v238, v96
	v_exp_f32_e32 v240, v97
	ds_read_b64_tr_b16 v[82:83], v92 offset:16384
	ds_read_b64_tr_b16 v[90:91], v92 offset:18432
	ds_read_b64_tr_b16 v[94:95], v92 offset:20480
	ds_read_b64_tr_b16 v[100:101], v92 offset:22528
	ds_read_b64_tr_b16 v[92:93], v102 offset:18432
	ds_read_b64_tr_b16 v[96:97], v102 offset:20480
	ds_read_b64_tr_b16 v[102:103], v102 offset:22528
	s_waitcnt lgkmcnt(6)
	v_mfma_f32_32x32x16_bf16 v[50:65], v[82:85], v[104:107], v[50:65]
	ds_read_b64_tr_b16 v[82:83], v110 offset:18432
	ds_read_b64_tr_b16 v[108:109], v110 offset:20480
	ds_read_b64_tr_b16 v[112:113], v110 offset:22528
	ds_read_b64_tr_b16 v[84:85], v114 offset:18432
	ds_read_b64_tr_b16 v[110:111], v114 offset:20480
	ds_read_b64_tr_b16 v[114:115], v114 offset:22528
	v_exp_f32_e32 v193, v66
	v_exp_f32_e32 v195, v67
	v_exp_f32_e32 v197, v68
	v_exp_f32_e32 v199, v69
	v_cvt_pk_bf16_f32 v66, v226, v228
	v_cvt_pk_bf16_f32 v67, v230, v232
	v_mfma_f32_32x32x16_bf16 v[18:33], v[86:89], v[104:107], v[18:33]
	v_cvt_pk_bf16_f32 v68, v234, v236
	v_cvt_pk_bf16_f32 v69, v238, v240
	v_exp_f32_e32 v201, v70
	v_exp_f32_e32 v203, v71
	v_exp_f32_e32 v205, v72
	v_exp_f32_e32 v207, v73
	v_exp_f32_e32 v227, v74
	s_waitcnt lgkmcnt(8)
	v_mfma_f32_32x32x16_bf16 v[50:65], v[90:93], v[66:69], v[50:65]
	v_exp_f32_e32 v229, v75
	v_exp_f32_e32 v231, v76
	v_exp_f32_e32 v233, v77
	v_exp_f32_e32 v235, v78
	v_exp_f32_e32 v237, v79
	v_exp_f32_e32 v239, v80
	v_exp_f32_e32 v241, v81
	s_waitcnt lgkmcnt(2)
	v_mfma_f32_32x32x16_bf16 v[18:33], v[82:85], v[66:69], v[18:33]
	v_cvt_pk_bf16_f32 v66, v193, v195
	v_cvt_pk_bf16_f32 v67, v197, v199
	v_cvt_pk_bf16_f32 v68, v201, v203
	v_cvt_pk_bf16_f32 v69, v205, v207
	v_add_f32_e64 v70, v192, v194
	v_add_f32_e64 v71, v193, v195
	v_add_f32_e32 v72, v196, v198
	v_add_f32_e32 v73, v197, v199
	v_add_f32_e32 v74, v204, v206
	v_add_f32_e32 v75, v205, v207
	v_mfma_f32_32x32x16_bf16 v[50:65], v[94:97], v[66:69], v[50:65]
	v_add_f32_e64 v70, v70, v72
	v_add_f32_e64 v71, v71, v73
	v_add_f32_e64 v72, v200, v202
	v_add_f32_e64 v73, v201, v203
	v_add_f32_e64 v76, v234, v236
	v_add_f32_e64 v77, v235, v237
	v_add_f32_e32 v72, v72, v74
	v_add_f32_e32 v73, v73, v75
	v_add_f32_e32 v74, v226, v228
	v_add_f32_e32 v75, v227, v229
	v_add_f32_e32 v78, v238, v240
	v_add_f32_e32 v79, v239, v241
	v_add_f32_e32 v70, v70, v72
	v_add_f32_e32 v71, v71, v73
	s_waitcnt lgkmcnt(1)
	v_mfma_f32_32x32x16_bf16 v[18:33], v[108:111], v[66:69], v[18:33]
	v_add_f32_e64 v66, v230, v232
	v_add_f32_e64 v67, v231, v233
	v_add_f32_e64 v76, v76, v78
	v_add_f32_e64 v77, v77, v79
	v_add_f32_e64 v74, v74, v66
	v_add_f32_e64 v75, v75, v67
	v_cvt_pk_bf16_f32 v66, v227, v229
	v_add_f32_e32 v72, v74, v76
	v_add_f32_e32 v73, v75, v77
	v_cvt_pk_bf16_f32 v67, v231, v233
	v_cvt_pk_bf16_f32 v68, v235, v237
	v_cvt_pk_bf16_f32 v69, v239, v241
	v_add_f32_e32 v70, v70, v72
	v_add_f32_e32 v71, v71, v73
	s_nop 0
	v_mfma_f32_32x32x16_bf16 v[50:65], v[100:103], v[66:69], v[50:65]
	v_add_f32_e32 v70, v70, v71
	ds_bpermute_b32 v71, v98, v70
	v_add_f32_e32 v181, v181, v70
	s_waitcnt lgkmcnt(1)
	v_mfma_f32_32x32x16_bf16 v[18:33], v[112:115], v[66:69], v[18:33]
	s_waitcnt lgkmcnt(0)
	v_add_f32_e32 v66, v70, v71
	v_cmp_lt_f32_e32 vcc, s68, v66
	s_cbranch_vccz .LBB0_803
; #define LAS3 __attribute__((address_space(3)))
; template <int MK> ...
;     ...
;   if (__builtin_amdgcn_ballot_w64(tot > 256.f) != 0) {
;     const float delta = fmaxf(__builtin_amdgcn_logf(tot), 0.f);
;     const float alpha = __builtin_amdgcn_exp2f(-delta);
;     st.m += delta; st.l *= alpha;
; #pragma unroll
;     for (int v = 0; v < 16; ++v) { st.cinit[v] -= delta; st.o0[v] *= alpha; st.o1[v] *= alpha; }
;   }
; template <int MODE>
; DI void attn_seq(const Params& p, int layer, char* smem, const int tid, const int nitems, bf16_t* ob, const int ostride) {
;     ...
;     for (int u = 0; u < d.nt; ++u) {
;       if (gvalid || !(k == nit - 1 && u == d.nt - 1)) asm volatile("s_waitcnt vmcnt(4)" ::: "memory");
;       else asm volatile("s_waitcnt vmcnt(0)" ::: "memory");
;       __builtin_amdgcn_s_barrier();
;       asm volatile("" ::: "memory");
;       if (gvalid) gen_issue();
;       LAS3 const char* Kb = lds + sc * ATT_STAGE;
;       LAS3 const char* Vb = Kb + 16384;
;       slast = sc;
;       sc = (sc == ATT_NST - 1) ? 0 : sc + 1;
	v_log_f32_e32 v66, v66
	s_nop 0
	v_max_f32_e32 v67, 0, v66
	v_exp_f32_e64 v66, -v67
	v_add_f32_e32 v182, v182, v67
	v_sub_f32_e32 v49, v49, v67
	v_sub_f32_e32 v48, v48, v67
	v_sub_f32_e32 v47, v47, v67
	v_sub_f32_e32 v46, v46, v67
	v_sub_f32_e32 v45, v45, v67
	v_mul_f32_e32 v181, v181, v66
	v_sub_f32_e32 v44, v44, v67
	v_sub_f32_e32 v43, v43, v67
	v_sub_f32_e32 v42, v42, v67
	v_sub_f32_e32 v41, v41, v67
	v_sub_f32_e32 v40, v40, v67
	v_sub_f32_e32 v39, v39, v67
	v_sub_f32_e32 v38, v38, v67
	v_sub_f32_e32 v37, v37, v67
	v_sub_f32_e32 v36, v36, v67
	v_sub_f32_e32 v35, v35, v67
	v_sub_f32_e32 v34, v34, v67
	v_pk_mul_f32 v[64:65], v[64:65], v[66:67] op_sel_hi:[1,0]
	v_pk_mul_f32 v[62:63], v[62:63], v[66:67] op_sel_hi:[1,0]
	v_pk_mul_f32 v[60:61], v[60:61], v[66:67] op_sel_hi:[1,0]
	v_pk_mul_f32 v[58:59], v[58:59], v[66:67] op_sel_hi:[1,0]
	v_pk_mul_f32 v[56:57], v[56:57], v[66:67] op_sel_hi:[1,0]
	v_pk_mul_f32 v[54:55], v[54:55], v[66:67] op_sel_hi:[1,0]
	v_pk_mul_f32 v[52:53], v[52:53], v[66:67] op_sel_hi:[1,0]
	v_pk_mul_f32 v[50:51], v[50:51], v[66:67] op_sel_hi:[1,0]
	v_pk_mul_f32 v[32:33], v[32:33], v[66:67] op_sel_hi:[1,0]
	v_pk_mul_f32 v[30:31], v[30:31], v[66:67] op_sel_hi:[1,0]
	v_pk_mul_f32 v[28:29], v[28:29], v[66:67] op_sel_hi:[1,0]
	v_pk_mul_f32 v[26:27], v[26:27], v[66:67] op_sel_hi:[1,0]
	v_pk_mul_f32 v[24:25], v[24:25], v[66:67] op_sel_hi:[1,0]
	v_pk_mul_f32 v[22:23], v[22:23], v[66:67] op_sel_hi:[1,0]
	v_pk_mul_f32 v[20:21], v[20:21], v[66:67] op_sel_hi:[1,0]
	v_pk_mul_f32 v[18:19], v[18:19], v[66:67] op_sel_hi:[1,0]
	s_branch .LBB0_803
.LBB0_806:
	s_and_b64 vcc, exec, s[70:71]
	s_cbranch_vccnz .Lm1_806_copy
	s_add_i32 s0, s87, 1
	s_cmp_lg_u32 s87, 2
	s_cselect_b32 s87, s0, 0
	s_add_i32 s21, s21, 1
	s_branch .LBB0_777

; template <int MK> ...
;   f32x16 s0 = qk_tile(k0, L, q0, q1, q2, q3, init);
;   f32x16 s1 = qk_tile(k1, L, q0, q1, q2, q3, init);
;   if (MK == 2) {
; #pragma unroll
;     for (int v = 0; v < 16; ++v) { s0[v] += b0[(v & 3) + 8 * (v >> 2)]; s1[v] += b1[(v & 3) + 8 * (v >> 2)]; }
;   }
;   if (MK == 1 && kb1 != 0x7fffffff) {
;     const int lo = max(0, sq - 128), hi = min(2047, sq + 128);
;     const int L0 = lo - kb0 - 4 * h, H0 = hi - kb0 - 4 * h, L1 = lo - kb1 - 4 * h, H1 = hi - kb1 - 4 * h;
; #pragma unroll
;     for (int v = 0; v < 16; ++v) {
;       const int cv = (v & 3) + 8 * (v >> 2);
;       s0[v] = (cv >= L0 && cv <= H0) ? s0[v] : -1e30f;
;       s1[v] = (cv >= L1 && cv <= H1) ? s1[v] : -1e30f;
;     }
;   }
; #pragma unroll
;   for (int v = 0; v < 16; ++v) s0[v] = __builtin_amdgcn_exp2f(s0[v]);
;   const float a0 = (s0[0] + s0[1]) + (s0[2] + s0[3]), a1 = (s0[4] + s0[5]) + (s0[6] + s0[7]);
;   const float a2 = (s0[8] + s0[9]) + (s0[10] + s0[11]), a3 = (s0[12] + s0[13]) + (s0[14] + s0[15]);
;   pv_tile(v0, L, s0, st.o0, st.o1);
; #pragma unroll
;   for (int v = 0; v < 16; ++v) s1[v] = __builtin_amdgcn_exp2f(s1[v]);
;   const float a4 = (s1[0] + s1[1]) + (s1[2] + s1[3]), a5 = (s1[4] + s1[5]) + (s1[6] + s1[7]);
;   const float a6 = (s1[8] + s1[9]) + (s1[10] + s1[11]), a7 = (s1[12] + s1[13]) + (s1[14] + s1[15]);
;   pv_tile(v1, L, s1, st.o0, st.o1);
;   const float sum = ((a0 + a1) + (a2 + a3)) + ((a4 + a5) + (a6 + a7));
;   st.l += sum;
;   const float tot = sum + __shfl_xor(sum, 32);
;   if (__builtin_amdgcn_ballot_w64(tot > 256.f) != 0) {
;     const float delta = fmaxf(__builtin_amdgcn_logf(tot), 0.f);
;     const float alpha = __builtin_amdgcn_exp2f(-delta);
;     st.m += delta; st.l *= alpha;
; #pragma unroll
;     for (int v = 0; v < 16; ++v) { st.cinit[v] -= delta; st.o0[v] *= alpha; st.o1[v] *= alpha; }
;   }
.LBB0_833:
	s_add_i32 s26, s25, s26
	v_add_u32_e32 v54, s26, v130
	ds_read_b128 v[50:53], v54
	ds_read_b128 v[106:109], v54 offset:4096
	v_add_u32_e32 v105, s26, v131
	v_add_u32_e32 v110, s26, v132
	v_add_u32_e32 v111, s26, v133
	v_add_u32_e32 v176, s26, v135
	v_add_u32_e32 v177, s26, v136
	v_add_u32_e32 v178, s26, v137
	s_waitcnt lgkmcnt(0)
	v_mfma_f32_32x32x16_bf16 v[66:81], v[50:53], v[82:85], v[34:49]
	ds_read_b128 v[50:53], v105
	s_waitcnt lgkmcnt(0)
	v_mfma_f32_32x32x16_bf16 v[66:81], v[50:53], v[86:89], v[66:81]
	ds_read_b128 v[50:53], v110
	s_waitcnt lgkmcnt(0)
	v_mfma_f32_32x32x16_bf16 v[66:81], v[50:53], v[90:93], v[66:81]
	v_mfma_f32_32x32x16_bf16 v[50:65], v[106:109], v[82:85], v[34:49]
	ds_read_b128 v[106:109], v111
	ds_read_b128 v[160:163], v105 offset:4096
	ds_read_b128 v[164:167], v110 offset:4096
	ds_read_b128 v[168:171], v111 offset:4096
	v_add_u32_e32 v105, s26, v134
	s_waitcnt lgkmcnt(0)
	v_mfma_f32_32x32x16_bf16 v[50:65], v[160:163], v[86:89], v[50:65]
	s_nop 0
	ds_read_b64_tr_b16 v[160:161], v105 offset:16384
	ds_read_b64_tr_b16 v[162:163], v176 offset:16384
	v_mfma_f32_32x32x16_bf16 v[50:65], v[164:167], v[90:93], v[50:65]
	v_mfma_f32_32x32x16_bf16 v[66:81], v[106:109], v[94:97], v[66:81]
	v_mfma_f32_32x32x16_bf16 v[50:65], v[168:171], v[94:97], v[50:65]
	s_nop 10
	v_exp_f32_e32 v116, v66
	v_exp_f32_e32 v120, v67
	v_exp_f32_e32 v118, v68
	v_exp_f32_e32 v124, v69
	v_exp_f32_e32 v108, v70
	v_exp_f32_e32 v112, v71
	v_exp_f32_e32 v110, v72
	v_exp_f32_e32 v114, v73
	ds_read_b64_tr_b16 v[164:165], v177 offset:16384
	ds_read_b64_tr_b16 v[166:167], v178 offset:16384
	ds_read_b64_tr_b16 v[172:173], v105 offset:18432
	ds_read_b64_tr_b16 v[174:175], v176 offset:18432
	ds_read_b64_tr_b16 v[66:67], v177 offset:18432
	ds_read_b64_tr_b16 v[68:69], v178 offset:18432
	v_exp_f32_e32 v117, v50
	v_exp_f32_e32 v121, v51
	v_exp_f32_e32 v119, v52
	v_exp_f32_e32 v125, v53
	v_cvt_pk_bf16_f32 v50, v116, v120
	v_cvt_pk_bf16_f32 v51, v118, v124
	v_cvt_pk_bf16_f32 v52, v108, v112
	v_cvt_pk_bf16_f32 v53, v110, v114
	v_exp_f32_e32 v70, v74
	v_exp_f32_e32 v74, v75
	s_waitcnt lgkmcnt(6)
	v_mfma_f32_32x32x16_bf16 v[18:33], v[160:163], v[50:53], v[18:33]
	v_exp_f32_e32 v72, v76
	v_exp_f32_e32 v106, v77
	v_exp_f32_e32 v76, v78
	v_exp_f32_e32 v78, v79
	v_exp_f32_e32 v80, v80
	v_exp_f32_e32 v122, v81
	v_exp_f32_e32 v109, v54
	s_waitcnt lgkmcnt(4)
	v_mfma_f32_32x32x16_bf16 v[2:17], v[164:167], v[50:53], v[2:17]
	v_exp_f32_e32 v113, v55
	v_exp_f32_e32 v111, v56
	v_exp_f32_e32 v115, v57
	ds_read_b64_tr_b16 v[50:51], v105 offset:20480
	v_cvt_pk_bf16_f32 v54, v70, v74
	v_cvt_pk_bf16_f32 v55, v72, v106
	v_cvt_pk_bf16_f32 v56, v76, v78
	v_cvt_pk_bf16_f32 v57, v80, v122
	v_exp_f32_e32 v71, v58
	v_exp_f32_e32 v75, v59
	s_waitcnt lgkmcnt(3)
	v_mfma_f32_32x32x16_bf16 v[18:33], v[172:175], v[54:57], v[18:33]
	v_exp_f32_e32 v73, v60
	v_exp_f32_e32 v107, v61
	v_exp_f32_e32 v77, v62
	v_exp_f32_e32 v79, v63
	v_exp_f32_e32 v81, v64
	v_exp_f32_e32 v123, v65
	ds_read_b64_tr_b16 v[52:53], v176 offset:20480
	ds_read_b64_tr_b16 v[58:59], v177 offset:20480
	ds_read_b64_tr_b16 v[60:61], v178 offset:20480
	ds_read_b64_tr_b16 v[62:63], v105 offset:22528
	ds_read_b64_tr_b16 v[64:65], v176 offset:22528
	ds_read_b64_tr_b16 v[160:161], v177 offset:22528
	ds_read_b64_tr_b16 v[162:163], v178 offset:22528
	s_waitcnt lgkmcnt(8)
	v_mfma_f32_32x32x16_bf16 v[2:17], v[66:69], v[54:57], v[2:17]
	v_add_f32_e64 v54, v116, v120
	v_add_f32_e64 v55, v117, v121
	v_add_f32_e64 v56, v118, v124
	v_add_f32_e64 v57, v119, v125
	v_add_f32_e64 v68, v72, v106
	v_add_f32_e64 v69, v73, v107
	v_add_f32_e32 v66, v54, v56
	v_add_f32_e32 v67, v55, v57
	v_cvt_pk_bf16_f32 v54, v117, v121
	v_cvt_pk_bf16_f32 v55, v119, v125
	v_cvt_pk_bf16_f32 v56, v109, v113
	v_cvt_pk_bf16_f32 v57, v111, v115
	s_waitcnt lgkmcnt(6)
	s_nop 0
	v_mfma_f32_32x32x16_bf16 v[18:33], v[50:53], v[54:57], v[18:33]
	v_add_f32_e64 v50, v108, v112
	v_add_f32_e64 v51, v109, v113
	v_add_f32_e64 v52, v110, v114
	v_add_f32_e64 v53, v111, v115
	v_add_f32_e64 v50, v50, v52
	v_add_f32_e64 v51, v51, v53
	v_add_f32_e32 v52, v70, v74
	v_add_f32_e32 v53, v71, v75
	v_add_f32_e32 v50, v66, v50
	v_add_f32_e32 v51, v67, v51
	v_add_f32_e32 v68, v52, v68
	v_add_f32_e32 v69, v53, v69
	s_waitcnt lgkmcnt(4)
	v_mfma_f32_32x32x16_bf16 v[2:17], v[58:61], v[54:57], v[2:17]
	v_add_f32_e64 v52, v76, v78
	v_add_f32_e64 v53, v77, v79
	v_add_f32_e64 v54, v80, v122
	v_add_f32_e64 v55, v81, v123
	v_add_f32_e64 v56, v52, v54
	v_add_f32_e64 v57, v53, v55
	v_cvt_pk_bf16_f32 v52, v71, v75
	v_add_f32_e32 v56, v68, v56
	v_add_f32_e32 v57, v69, v57
	v_cvt_pk_bf16_f32 v53, v73, v107
	v_cvt_pk_bf16_f32 v54, v77, v79
	v_cvt_pk_bf16_f32 v55, v81, v123
	v_add_f32_e32 v50, v50, v56
	v_add_f32_e32 v51, v51, v57
	s_waitcnt lgkmcnt(2)
	v_mfma_f32_32x32x16_bf16 v[18:33], v[62:65], v[52:55], v[18:33]
	v_add_f32_e32 v50, v50, v51
	ds_bpermute_b32 v51, v103, v50
	v_add_f32_e32 v101, v101, v50
	s_waitcnt lgkmcnt(0)
	v_add_f32_e32 v50, v50, v51
	v_mfma_f32_32x32x16_bf16 v[2:17], v[160:163], v[52:55], v[2:17]
	v_cmp_lt_f32_e32 vcc, s68, v50
	s_cbranch_vccz .LBB0_832
	v_log_f32_e32 v50, v50
	s_nop 0
	v_max_f32_e32 v51, 0, v50
	v_exp_f32_e64 v50, -v51
	v_sub_f32_e32 v49, v49, v51
	v_sub_f32_e32 v48, v48, v51
	v_sub_f32_e32 v47, v47, v51
	v_sub_f32_e32 v46, v46, v51
	v_sub_f32_e32 v45, v45, v51
	v_sub_f32_e32 v44, v44, v51
	v_mul_f32_e32 v101, v101, v50
	v_sub_f32_e32 v43, v43, v51
	v_sub_f32_e32 v42, v42, v51
	v_sub_f32_e32 v41, v41, v51
	v_sub_f32_e32 v40, v40, v51
	v_sub_f32_e32 v39, v39, v51
	v_sub_f32_e32 v38, v38, v51
	v_sub_f32_e32 v37, v37, v51
	v_sub_f32_e32 v36, v36, v51
	v_sub_f32_e32 v35, v35, v51
	v_sub_f32_e32 v34, v34, v51
	v_pk_mul_f32 v[32:33], v[32:33], v[50:51] op_sel_hi:[1,0]
	v_pk_mul_f32 v[30:31], v[30:31], v[50:51] op_sel_hi:[1,0]
	v_pk_mul_f32 v[28:29], v[28:29], v[50:51] op_sel_hi:[1,0]
	v_pk_mul_f32 v[26:27], v[26:27], v[50:51] op_sel_hi:[1,0]
	v_pk_mul_f32 v[24:25], v[24:25], v[50:51] op_sel_hi:[1,0]
	v_pk_mul_f32 v[22:23], v[22:23], v[50:51] op_sel_hi:[1,0]
	v_pk_mul_f32 v[20:21], v[20:21], v[50:51] op_sel_hi:[1,0]
	v_pk_mul_f32 v[18:19], v[18:19], v[50:51] op_sel_hi:[1,0]
	v_pk_mul_f32 v[16:17], v[16:17], v[50:51] op_sel_hi:[1,0]
	v_pk_mul_f32 v[14:15], v[14:15], v[50:51] op_sel_hi:[1,0]
	v_pk_mul_f32 v[12:13], v[12:13], v[50:51] op_sel_hi:[1,0]
	v_pk_mul_f32 v[10:11], v[10:11], v[50:51] op_sel_hi:[1,0]
	v_pk_mul_f32 v[8:9], v[8:9], v[50:51] op_sel_hi:[1,0]
	v_pk_mul_f32 v[6:7], v[6:7], v[50:51] op_sel_hi:[1,0]
	v_pk_mul_f32 v[4:5], v[4:5], v[50:51] op_sel_hi:[1,0]
	v_pk_mul_f32 v[2:3], v[2:3], v[50:51] op_sel_hi:[1,0]
	s_branch .LBB0_832

; template <int MODE>
; DI void attn_seq(const Params& p, int layer, char* smem, const int tid, const int nitems, bf16_t* ob, const int ostride) {
;     ...
;     const bf16_t* qp = p.qkvg + (size_t)tq * NW + hq * 64 + h * 8;
;     ...
;     float lsum = st.l + __shfl_xor(st.l, 32);
;     if (isA) lsum += __builtin_amdgcn_exp2f(p.a_sink[jl * 16 + hq] * LOG2E - st.m);
;     const float inv = 1.f / lsum;
;     LAS3 char* scr = lds + ATT_GATE + wv * 4096;
;     u32x4 gv0, gv1, gv2, gv3;
;     gv0 = *(LAS3 const u32x4*)(scr + 0 * 1024 + lane * 16); gv1 = *(LAS3 const u32x4*)(scr + 1 * 1024 + lane * 16);
;     gv2 = *(LAS3 const u32x4*)(scr + 2 * 1024 + lane * 16); gv3 = *(LAS3 const u32x4*)(scr + 3 * 1024 + lane * 16);
;     asm volatile("s_waitcnt lgkmcnt(0)" ::: "memory");
;     {
;       const int swr = swz(r & 15);
; #pragma unroll
;       for (int g4 = 0; g4 < 4; ++g4) {
;         u32x2 w0, w1;
;         w0[0] = pk2(st.o0[4 * g4 + 0] * inv, st.o0[4 * g4 + 1] * inv); w0[1] = pk2(st.o0[4 * g4 + 2] * inv, st.o0[4 * g4 + 3] * inv);
;         w1[0] = pk2(st.o1[4 * g4 + 0] * inv, st.o1[4 * g4 + 1] * inv); w1[1] = pk2(st.o1[4 * g4 + 2] * inv, st.o1[4 * g4 + 3] * inv);
;         *(LAS3 u32x2*)(scr + r * 128 + ((g4 ^ swr) * 16) + 8 * h) = w0;
;         *(LAS3 u32x2*)(scr + r * 128 + (((4 + g4) ^ swr) * 16) + 8 * h) = w1;
;       }
;     }
; #pragma unroll
;     for (int pass = 0; pass < 4; ++pass) {
;       const int row = (lane >> 3) + 8 * pass, piece = lane & 7;
;       const u32x4 ov = *(LAS3 const u32x4*)(scr + row * 128 + ((piece ^ swz(row & 15)) * 16));
;       int tqr;
;       if (MODE == 0) tqr = d.b * 2048 + q0i + row;
;       else if (MODE == 1) tqr = d.b * 2048 + ((item & 7) * 4 + 2 * (wv >> 2) + (row >> 4)) * 64 + 16 * (wv & 3) + (row & 15);
;       else if (MODE == 2) tqr = TL + d.b * 256 + (item & 3) * 64 + 32 * (wv >> 2) + row;
;       else tqr = TL + d.b * 256 + wv * 32 + row;
;       const u32x4 gv = (pass == 0) ? gv0 : (pass == 1) ? gv1 : (pass == 2) ? gv2 : gv3;
;       uint4 w;
;       w.x = pk2(bflo(ov[0]) * bflo(gv[0]), bfhi(ov[0]) * bfhi(gv[0]));
;       w.y = pk2(bflo(ov[1]) * bflo(gv[1]), bfhi(ov[1]) * bfhi(gv[1]));
;       w.z = pk2(bflo(ov[2]) * bflo(gv[2]), bfhi(ov[2]) * bfhi(gv[2]));
;       w.w = pk2(bflo(ov[3]) * bflo(gv[3]), bfhi(ov[3]) * bfhi(gv[3]));
;       *(uint4*)(ob + (size_t)tqr * ostride + hq * 64 + piece * 8) = w;
.LBB0_845:
	s_add_i32 s100, s96, 1
	s_cmp_ge_i32 s100, s7
	s_cbranch_scc1 .Lm0_noprefetch
	s_add_i32 s100, s100, s6
	s_lshl_b32 s101, s100, 6
	s_and_b32 s101, s101, 0x7c0
	s_add_i32 s101, s101, s85
	s_lshl_b32 vcc_lo, s100, 4
	s_and_b32 vcc_lo, vcc_lo, 0xfffff800
	s_add_i32 s101, s101, vcc_lo
	s_lshr_b32 s100, s100, 3
	s_and_b32 s100, s100, 12
	s_or_b32 s100, s100, s84
	s_lshl_b32 s100, s100, 7
	v_or_b32_e32 v100, s101, v133
	v_mov_b64_e32 v[98:99], s[38:39]
	s_mov_b32 s101, 0
	v_mad_i64_i32 v[96:97], vcc, v100, s92, v[98:99]
	v_mov_b32_e32 v102, v118
	v_mov_b32_e32 v103, 0
	v_lshl_add_u64 v[96:97], v[96:97], 0, s[100:101]
	v_lshl_add_u64 v[96:97], v[96:97], 0, v[102:103]
	global_load_dwordx4 v[108:111], v[96:97], off offset:96
	global_load_dwordx4 v[104:107], v[96:97], off offset:64
	global_load_dwordx4 v[100:103], v[96:97], off offset:32
	global_load_dwordx4 v[96:99], v[96:97], off
.Lm0_noprefetch:
	s_or_b32 s0, s11, s88
	s_ashr_i32 s1, s0, 31
	v_readlane_b32 s16, v255, 36
	s_lshl_b64 s[0:1], s[0:1], 2
	v_readlane_b32 s20, v255, 40
	v_and_b32_e32 v2, 64, v214
	v_readlane_b32 s21, v255, 41
	s_add_u32 s0, s20, s0
	v_xor_b32_e32 v0, 32, v214
	v_add_u32_e32 v2, 64, v2
	s_addc_u32 s1, s21, s1
	v_cmp_lt_i32_e32 vcc, v0, v2
	s_mov_b32 s0, 0x3fb8aa3b
	v_cndmask_b32_e32 v0, v214, v0, vcc
	v_lshlrev_b32_e32 v0, 2, v0
	ds_bpermute_b32 v0, v0, v171
	s_lshl_b32 s78, s10, 1
	s_add_i32 s96, s96, 1
	s_cmp_ge_i32 s96, s7
	v_readlane_b32 s17, v255, 37
	s_waitcnt lgkmcnt(0)
	v_add_f32_e32 v0, v171, v0
	v_readlane_b32 s18, v255, 38
	v_readlane_b32 s19, v255, 39
	v_readlane_b32 s22, v255, 42
	v_readlane_b32 s23, v255, 43
	s_nop 0
	v_fma_f32 v2, v183, s0, -v117
	v_exp_f32_e32 v2, v2
	s_nop 0
	v_add_f32_e32 v0, v0, v2
	v_div_scale_f32 v2, s[0:1], v0, v0, 1.0
	v_rcp_f32_e32 v3, v2
	s_nop 0
	v_fma_f32 v4, -v2, v3, 1.0
	v_fmac_f32_e32 v3, v4, v3
	v_div_scale_f32 v4, vcc, 1.0, v0, 1.0
	v_mul_f32_e32 v5, v4, v3
	v_fma_f32 v6, -v2, v5, v4
	v_fmac_f32_e32 v5, v6, v3
	v_fma_f32 v2, -v2, v5, v4
	v_div_fmas_f32 v2, v2, v3, v5
	v_div_fixup_f32 v0, v2, v0, 1.0
	v_pk_mul_f32 v[14:15], v[32:33], v[0:1] op_sel_hi:[1,0]
	v_pk_mul_f32 v[32:33], v[34:35], v[0:1] op_sel_hi:[1,0]
	v_pk_mul_f32 v[16:17], v[16:17], v[0:1] op_sel_hi:[1,0]
	v_pk_mul_f32 v[18:19], v[18:19], v[0:1] op_sel_hi:[1,0]
	v_cvt_pk_bf16_f32 v14, v14, v15
	v_cvt_pk_bf16_f32 v15, v32, v33
	v_cvt_pk_bf16_f32 v16, v16, v17
	v_cvt_pk_bf16_f32 v17, v18, v19
	v_add_u32_e32 v18, v153, v154
	ds_read_b128 v[48:51], v158
	ds_read_b128 v[10:13], v158 offset:1024
	ds_read_b128 v[6:9], v158 offset:2048
	ds_read_b128 v[2:5], v158 offset:3072
	s_waitcnt lgkmcnt(0)
	ds_write_b64 v18, v[14:15]
	ds_write_b64 v159, v[16:17]
	v_pk_mul_f32 v[14:15], v[36:37], v[0:1] op_sel_hi:[1,0]
	v_pk_mul_f32 v[16:17], v[38:39], v[0:1] op_sel_hi:[1,0]
	v_cvt_pk_bf16_f32 v14, v14, v15
	v_cvt_pk_bf16_f32 v15, v16, v17
	v_pk_mul_f32 v[16:17], v[20:21], v[0:1] op_sel_hi:[1,0]
	v_pk_mul_f32 v[18:19], v[22:23], v[0:1] op_sel_hi:[1,0]
	v_cvt_pk_bf16_f32 v16, v16, v17
	v_cvt_pk_bf16_f32 v17, v18, v19
	ds_write_b64 v160, v[14:15]
	ds_write_b64 v161, v[16:17]
	v_pk_mul_f32 v[14:15], v[40:41], v[0:1] op_sel_hi:[1,0]
	v_pk_mul_f32 v[16:17], v[42:43], v[0:1] op_sel_hi:[1,0]
	v_cvt_pk_bf16_f32 v14, v14, v15
	v_cvt_pk_bf16_f32 v15, v16, v17
	v_pk_mul_f32 v[16:17], v[24:25], v[0:1] op_sel_hi:[1,0]
	v_pk_mul_f32 v[18:19], v[26:27], v[0:1] op_sel_hi:[1,0]
	v_cvt_pk_bf16_f32 v16, v16, v17
	v_cvt_pk_bf16_f32 v17, v18, v19
	ds_write_b64 v162, v[14:15]
	ds_write_b64 v163, v[16:17]
	v_pk_mul_f32 v[14:15], v[44:45], v[0:1] op_sel_hi:[1,0]
	v_pk_mul_f32 v[16:17], v[46:47], v[0:1] op_sel_hi:[1,0]
	v_cvt_pk_bf16_f32 v14, v14, v15
	v_cvt_pk_bf16_f32 v15, v16, v17
	v_pk_mul_f32 v[16:17], v[28:29], v[0:1] op_sel_hi:[1,0]
	v_pk_mul_f32 v[18:19], v[30:31], v[0:1] op_sel_hi:[1,0]
	v_cvt_pk_bf16_f32 v16, v16, v17
	v_cvt_pk_bf16_f32 v17, v18, v19
	ds_write_b64 v164, v[14:15]
	ds_write_b64 v165, v[16:17]
	ds_read_b128 v[14:17], v166
	s_waitcnt lgkmcnt(12)
	v_lshlrev_b32_e32 v22, 16, v48
	v_and_b32_e32 v23, 0xffff0000, v48
	v_lshl_add_u64 v[18:19], v[114:115], 0, s[78:79]
	v_or_b32_e32 v0, s13, v155
	s_waitcnt lgkmcnt(0)
	v_lshlrev_b32_e32 v20, 16, v14
	v_and_b32_e32 v21, 0xffff0000, v14
	v_pk_mul_f32 v[20:21], v[22:23], v[20:21]
	v_lshlrev_b32_e32 v22, 16, v49
	v_cvt_pk_bf16_f32 v14, v20, v21
	v_lshlrev_b32_e32 v20, 16, v15
	v_and_b32_e32 v21, 0xffff0000, v15
	v_and_b32_e32 v23, 0xffff0000, v49
	v_pk_mul_f32 v[20:21], v[22:23], v[20:21]
	v_lshlrev_b32_e32 v22, 16, v50
	v_cvt_pk_bf16_f32 v15, v20, v21
	v_lshlrev_b32_e32 v20, 16, v16
	v_and_b32_e32 v21, 0xffff0000, v16
	v_and_b32_e32 v23, 0xffff0000, v50
	v_pk_mul_f32 v[20:21], v[22:23], v[20:21]
	v_lshlrev_b32_e32 v22, 16, v51
	v_cvt_pk_bf16_f32 v16, v20, v21
	v_lshlrev_b32_e32 v20, 16, v17
	v_and_b32_e32 v21, 0xffff0000, v17
	v_and_b32_e32 v23, 0xffff0000, v51
	v_pk_mul_f32 v[20:21], v[22:23], v[20:21]
	v_lshlrev_b32_e32 v22, 16, v10
	v_cvt_pk_bf16_f32 v17, v20, v21
	v_lshl_add_u64 v[20:21], v[18:19], 0, v[120:121]
	global_store_dwordx4 v[20:21], v[14:17], off
	ds_read_b128 v[14:17], v167
	v_and_b32_e32 v23, 0xffff0000, v10
	s_waitcnt lgkmcnt(0)
; #define LAS3 __attribute__((address_space(3)))
; template <int MODE>
; DI void attn_seq(const Params& p, int layer, char* smem, const int tid, const int nitems, bf16_t* ob, const int ostride) {
;     ...
;   for (int k = 0; k < nit; ++k) {
;     const int item = item0 + k;
;     const ItemD d = item_desc<MODE>(item);
;     int hq, tq, q0i = 0, rq = 0, cq = 0, wr_lo = 0, wr_hi = 0;
;     if (MODE == 0) { hq = d.hk * 4 + (wv & 3); q0i = (item & 31) * 64 + 32 * (wv >> 2); tq = d.b * 2048 + q0i + r; }
;     else if (MODE == 1) {
;       hq = d.hk; const int rw = (item & 7) * 4 + 2 * (wv >> 2);
;       rq = rw + (r >> 4); cq = 16 * (wv & 3) + (r & 15); tq = d.b * 2048 + rq * 64 + cq;
;       wr_lo = clampi(rw - 4, 0, 24); wr_hi = clampi(rw - 3, 0, 24) + 7;
;     } else if (MODE == 2) { hq = d.hk * 4 + (wv & 3); tq = TL + d.b * 256 + (item & 3) * 64 + 32 * (wv >> 2) + r; }
;     else { hq = d.hk; tq = TL + d.b * 256 + wv * 32 + r; }
;     {
; #pragma unroll
;       for (int pass = 0; pass < 4; ++pass) {
;         const int row = (lane >> 3) + 8 * pass;
;         int tqr;
;         if (MODE == 0) tqr = d.b * 2048 + q0i + row;
;         else if (MODE == 1) tqr = d.b * 2048 + ((item & 7) * 4 + 2 * (wv >> 2) + (row >> 4)) * 64 + 16 * (wv & 3) + (row & 15);
;     ...
; #pragma unroll
;     for (int pass = 0; pass < 4; ++pass) {
;       const int row = (lane >> 3) + 8 * pass, piece = lane & 7;
;       const u32x4 ov = *(LAS3 const u32x4*)(scr + row * 128 + ((piece ^ swz(row & 15)) * 16));
;       int tqr;
;       if (MODE == 0) tqr = d.b * 2048 + q0i + row;
;       else if (MODE == 1) tqr = d.b * 2048 + ((item & 7) * 4 + 2 * (wv >> 2) + (row >> 4)) * 64 + 16 * (wv & 3) + (row & 15);
;       else if (MODE == 2) tqr = TL + d.b * 256 + (item & 3) * 64 + 32 * (wv >> 2) + row;
;       else tqr = TL + d.b * 256 + wv * 32 + row;
;       const u32x4 gv = (pass == 0) ? gv0 : (pass == 1) ? gv1 : (pass == 2) ? gv2 : gv3;
;       uint4 w;
;       w.x = pk2(bflo(ov[0]) * bflo(gv[0]), bfhi(ov[0]) * bfhi(gv[0]));
;       w.y = pk2(bflo(ov[1]) * bflo(gv[1]), bfhi(ov[1]) * bfhi(gv[1]));
;       w.z = pk2(bflo(ov[2]) * bflo(gv[2]), bfhi(ov[2]) * bfhi(gv[2]));
;       w.w = pk2(bflo(ov[3]) * bflo(gv[3]), bfhi(ov[3]) * bfhi(gv[3]));
;       *(uint4*)(ob + (size_t)tqr * ostride + hq * 64 + piece * 8) = w;
;     }
;     asm volatile("s_waitcnt lgkmcnt(0)" ::: "memory");
	v_lshlrev_b32_e32 v20, 16, v14
	v_and_b32_e32 v21, 0xffff0000, v14
	v_pk_mul_f32 v[20:21], v[22:23], v[20:21]
	v_lshlrev_b32_e32 v14, 16, v15
	v_cvt_pk_bf16_f32 v10, v20, v21
	v_and_b32_e32 v15, 0xffff0000, v15
	v_lshlrev_b32_e32 v20, 16, v11
	v_and_b32_e32 v21, 0xffff0000, v11
	v_pk_mul_f32 v[14:15], v[20:21], v[14:15]
	v_lshlrev_b32_e32 v20, 16, v12
	v_cvt_pk_bf16_f32 v11, v14, v15
	v_lshlrev_b32_e32 v14, 16, v16
	v_and_b32_e32 v15, 0xffff0000, v16
	v_and_b32_e32 v21, 0xffff0000, v12
	v_pk_mul_f32 v[14:15], v[20:21], v[14:15]
	v_lshlrev_b32_e32 v16, 16, v13
	v_cvt_pk_bf16_f32 v12, v14, v15
	v_lshlrev_b32_e32 v14, 16, v17
	v_and_b32_e32 v15, 0xffff0000, v17
	v_and_b32_e32 v17, 0xffff0000, v13
	v_pk_mul_f32 v[14:15], v[16:17], v[14:15]
	v_lshlrev_b32_e32 v16, 16, v6
	v_cvt_pk_bf16_f32 v13, v14, v15
	v_mad_i64_i32 v[14:15], s[0:1], v0, s92, v[18:19]
	global_store_dwordx4 v[14:15], v[10:13], off
	ds_read_b128 v[10:13], v168
	v_and_b32_e32 v17, 0xffff0000, v6
	v_or_b32_e32 v0, s13, v156
	s_waitcnt lgkmcnt(0)
	v_lshlrev_b32_e32 v14, 16, v10
	v_and_b32_e32 v15, 0xffff0000, v10
	v_pk_mul_f32 v[14:15], v[16:17], v[14:15]
	v_lshlrev_b32_e32 v10, 16, v11
	v_cvt_pk_bf16_f32 v6, v14, v15
	v_and_b32_e32 v11, 0xffff0000, v11
	v_lshlrev_b32_e32 v14, 16, v7
	v_and_b32_e32 v15, 0xffff0000, v7
	v_pk_mul_f32 v[10:11], v[14:15], v[10:11]
	v_lshlrev_b32_e32 v14, 16, v8
	v_cvt_pk_bf16_f32 v7, v10, v11
	v_lshlrev_b32_e32 v10, 16, v12
	v_and_b32_e32 v11, 0xffff0000, v12
	v_and_b32_e32 v15, 0xffff0000, v8
	v_pk_mul_f32 v[10:11], v[14:15], v[10:11]
	v_lshlrev_b32_e32 v12, 16, v9
	v_cvt_pk_bf16_f32 v8, v10, v11
	v_lshlrev_b32_e32 v10, 16, v13
	v_and_b32_e32 v11, 0xffff0000, v13
	v_and_b32_e32 v13, 0xffff0000, v9
	v_pk_mul_f32 v[10:11], v[12:13], v[10:11]
	v_lshlrev_b32_e32 v12, 16, v2
	v_cvt_pk_bf16_f32 v9, v10, v11
	v_mad_i64_i32 v[10:11], s[0:1], v0, s92, v[18:19]
	global_store_dwordx4 v[10:11], v[6:9], off
	ds_read_b128 v[6:9], v169
	v_and_b32_e32 v13, 0xffff0000, v2
	v_or_b32_e32 v0, s13, v157
	s_waitcnt lgkmcnt(0)
	v_lshlrev_b32_e32 v10, 16, v6
	v_and_b32_e32 v11, 0xffff0000, v6
	v_pk_mul_f32 v[10:11], v[12:13], v[10:11]
	v_lshlrev_b32_e32 v6, 16, v7
	v_cvt_pk_bf16_f32 v2, v10, v11
	v_and_b32_e32 v7, 0xffff0000, v7
	v_lshlrev_b32_e32 v10, 16, v3
	v_and_b32_e32 v11, 0xffff0000, v3
	v_pk_mul_f32 v[6:7], v[10:11], v[6:7]
	v_lshlrev_b32_e32 v10, 16, v4
	v_cvt_pk_bf16_f32 v3, v6, v7
	v_lshlrev_b32_e32 v6, 16, v8
	v_and_b32_e32 v7, 0xffff0000, v8
	v_and_b32_e32 v11, 0xffff0000, v4
	v_pk_mul_f32 v[6:7], v[10:11], v[6:7]
	v_lshlrev_b32_e32 v8, 16, v5
	v_cvt_pk_bf16_f32 v4, v6, v7
	v_lshlrev_b32_e32 v6, 16, v9
	v_and_b32_e32 v7, 0xffff0000, v9
	v_and_b32_e32 v9, 0xffff0000, v5
	v_pk_mul_f32 v[6:7], v[8:9], v[6:7]
	s_nop 0
	v_cvt_pk_bf16_f32 v5, v6, v7
	v_mad_i64_i32 v[6:7], s[0:1], v0, s92, v[18:19]
	global_store_dwordx4 v[6:7], v[2:5], off
	s_waitcnt lgkmcnt(0)
	s_cbranch_scc1 .LBB0_875
.LBB0_846:
	s_add_i32 s0, s96, s6
	s_lshl_b32 s1, s0, 6
	s_and_b32 s20, s1, 0x7c0
	s_lshr_b32 s1, s0, 3
	s_lshl_b32 s0, s0, 4
	s_add_i32 s16, s20, s85
	s_and_b32 s0, s0, 0xfffff800
	s_and_b32 s1, s1, 12
	s_add_i32 s13, s16, s0
	s_or_b32 s11, s1, s84
	v_or_b32_e32 v0, s13, v134
	v_mov_b64_e32 v[2:3], s[38:39]
	v_mad_i64_i32 v[4:5], s[0:1], v0, s92, v[2:3]
	s_lshl_b32 s78, s11, 7
	v_lshl_add_u64 v[4:5], v[4:5], 0, s[78:79]
	v_mov_b32_e32 v117, v1
	v_lshl_add_u64 v[4:5], v[4:5], 0, v[116:117]
	s_mov_b64 s[14:15], 0xc00
	s_mov_b32 m0, s86
	v_lshl_add_u64 v[4:5], v[4:5], 0, s[14:15]
	global_load_lds_dwordx4 v[4:5], off
	v_or_b32_e32 v4, 8, v0
	v_mad_i64_i32 v[4:5], s[0:1], v4, s92, v[2:3]
	v_lshl_add_u64 v[4:5], v[4:5], 0, s[78:79]
	v_lshl_add_u64 v[4:5], v[4:5], 0, v[116:117]
	v_lshl_add_u64 v[4:5], v[4:5], 0, s[14:15]
	s_add_i32 m0, s86, 0x400
	v_mov_b32_e32 v119, v1
	global_load_lds_dwordx4 v[4:5], off
	v_or_b32_e32 v4, 16, v0
	v_mad_i64_i32 v[4:5], s[0:1], v4, s92, v[2:3]
	v_lshl_add_u64 v[4:5], v[4:5], 0, s[78:79]
	v_lshl_add_u64 v[4:5], v[4:5], 0, v[116:117]
	v_lshl_add_u64 v[4:5], v[4:5], 0, s[14:15]
	s_add_i32 m0, s86, 0x800
	v_mad_i64_i32 v[120:121], s[0:1], v0, s92, 0
	global_load_lds_dwordx4 v[4:5], off
	v_or_b32_e32 v4, 24, v0
	v_mad_i64_i32 v[4:5], s[0:1], v4, s92, v[2:3]
	v_lshl_add_u64 v[4:5], v[4:5], 0, s[78:79]
	v_lshl_add_u64 v[4:5], v[4:5], 0, v[116:117]
	v_lshl_add_u64 v[4:5], v[4:5], 0, s[14:15]
	s_add_i32 m0, s86, 0xc00
	v_or_b32_e32 v0, s16, v133
	global_load_lds_dwordx4 v[4:5], off
	v_readlane_b32 s100, v255, 40
	v_readlane_b32 s101, v255, 41
	s_cmp_lg_u32 s96, 0
	s_cbranch_scc1 .Lm0_skipq
	v_or_b32_e32 v4, s13, v133
	v_mad_i64_i32 v[2:3], s[0:1], v4, s92, v[2:3]
	v_lshl_add_u64 v[2:3], v[2:3], 0, s[78:79]
	v_lshl_add_u64 v[2:3], v[2:3], 0, v[118:119]
	global_load_dwordx4 v[96:99], v[2:3], off
	global_load_dwordx4 v[100:103], v[2:3], off offset:32
	global_load_dwordx4 v[104:107], v[2:3], off offset:64
	global_load_dwordx4 v[108:111], v[2:3], off offset:96
.Lm0_skipq:
	v_mov_b32_e32 v183, s11
	v_or_b32_e32 v183, s88, v183
	v_lshlrev_b32_e32 v183, 2, v183
	s_nop 1
	global_load_dword v183, v183, s[100:101]
	s_lshl_b32 s10, s11, 6
	s_addk_i32 s20, 0xff80
	v_max_i32_e32 v2, 0x80, v0
	v_min_i32_e32 v0, 0x77f, v0
	v_mov_b32_e32 v14, v1
	v_mov_b32_e32 v15, v1
	s_cmp_lg_u32 s96, s87
	v_add_u32_e32 v119, 0xffffff80, v2
	v_add_u32_e32 v170, 0x80, v0
	v_mov_b32_e32 v0, v1
	v_mov_b32_e32 v2, v1
	v_mov_b32_e32 v3, v1
	v_mov_b32_e32 v4, v1
	v_mov_b32_e32 v5, v1
	v_mov_b32_e32 v6, v1
	v_mov_b32_e32 v7, v1
	v_mov_b32_e32 v8, v1
	v_mov_b32_e32 v9, v1
	v_mov_b32_e32 v10, v1
	v_mov_b32_e32 v11, v1
	v_mov_b32_e32 v12, v1
	v_mov_b32_e32 v13, v1
	v_mov_b64_e32 v[62:63], v[14:15]
	v_mov_b64_e32 v[30:31], v[14:15]
	v_mov_b64_e32 v[46:47], v[14:15]
	s_cselect_b64 s[14:15], -1, 0
	s_add_i32 s21, s16, 0x9f
	s_add_i32 s22, s16, 0xffffff80
	s_add_i32 s23, s16, 0xffffff9f
	s_add_i32 s24, s16, 0x41
	v_mov_b32_e32 v171, 0
	s_mov_b32 s25, 0
	v_mov_b32_e32 v117, 0
	v_mov_b64_e32 v[60:61], v[12:13]
	v_mov_b64_e32 v[58:59], v[10:11]
	v_mov_b64_e32 v[56:57], v[8:9]
	v_mov_b64_e32 v[54:55], v[6:7]
	v_mov_b64_e32 v[52:53], v[4:5]
	v_mov_b64_e32 v[50:51], v[2:3]
	v_mov_b64_e32 v[48:49], v[0:1]
	v_mov_b64_e32 v[28:29], v[12:13]
	v_mov_b64_e32 v[26:27], v[10:11]
	v_mov_b64_e32 v[24:25], v[8:9]
	v_mov_b64_e32 v[22:23], v[6:7]
	v_mov_b64_e32 v[20:21], v[4:5]
	v_mov_b64_e32 v[18:19], v[2:3]
	v_mov_b64_e32 v[16:17], v[0:1]
	v_mov_b64_e32 v[44:45], v[12:13]
	v_mov_b64_e32 v[42:43], v[10:11]
	v_mov_b64_e32 v[40:41], v[8:9]
	v_mov_b64_e32 v[38:39], v[6:7]
	v_mov_b64_e32 v[36:37], v[4:5]
	v_mov_b64_e32 v[34:35], v[2:3]
	v_mov_b64_e32 v[32:33], v[0:1]
	s_cmp_lg_u32 s96, 0
	s_cbranch_scc1 .LBB0_848
	s_waitcnt vmcnt(0)
	s_branch .LBB0_848

; #define LAS3 __attribute__((address_space(3)))
; DI f32x16 qk_tile(LAS3 const char* kb, const AttnLane& L, const bf16x8& q0, const bf16x8& q1, const bf16x8& q2, const bf16x8& q3, const f32x16& init) {
;   f32x16 s = __builtin_amdgcn_mfma_f32_32x32x16_bf16(*(LAS3 const bf16x8*)(kb + L.kr0), q0, init, 0, 0, 0);
;   s = __builtin_amdgcn_mfma_f32_32x32x16_bf16(*(LAS3 const bf16x8*)(kb + L.kr1), q1, s, 0, 0, 0);
;   s = __builtin_amdgcn_mfma_f32_32x32x16_bf16(*(LAS3 const bf16x8*)(kb + L.kr2), q2, s, 0, 0, 0);
;   s = __builtin_amdgcn_mfma_f32_32x32x16_bf16(*(LAS3 const bf16x8*)(kb + L.kr3), q3, s, 0, 0, 0);
;   return s;
; }
; template <int MK> ...
;     ...
;   if (MK == 1 && kb1 != 0x7fffffff) {
;     const int lo = max(0, sq - 128), hi = min(2047, sq + 128);
;     const int L0 = lo - kb0 - 4 * h, H0 = hi - kb0 - 4 * h, L1 = lo - kb1 - 4 * h, H1 = hi - kb1 - 4 * h;
; #pragma unroll
;     for (int v = 0; v < 16; ++v) {
;       const int cv = (v & 3) + 8 * (v >> 2);
;       s0[v] = (cv >= L0 && cv <= H0) ? s0[v] : -1e30f;
;       s1[v] = (cv >= L1 && cv <= H1) ? s1[v] : -1e30f;
;     }
;   }
.LBB0_870:
	s_lshl_b32 s0, s33, 13
	s_add_i32 s33, s26, s0
	v_add_u32_e32 v0, s33, v139
	v_add_u32_e32 v6, s33, v140
	ds_read_b128 v[2:5], v0
	v_add_u32_e32 v7, s33, v141
	ds_read_b128 v[184:187], v6
	v_add_u32_e32 v8, s33, v142
	ds_read_b128 v[188:191], v7
	ds_read_b128 v[192:195], v8
	ds_read_b128 v[196:199], v0 offset:4096
	ds_read_b128 v[200:203], v6 offset:4096
	ds_read_b128 v[204:207], v7 offset:4096
	ds_read_b128 v[226:229], v8 offset:4096
	s_cmp_eq_u32 s69, 0x7fffffff
	s_waitcnt lgkmcnt(7)
	v_mfma_f32_32x32x16_bf16 v[80:95], v[2:5], v[96:99], v[48:63]
	s_waitcnt lgkmcnt(6)
	v_mfma_f32_32x32x16_bf16 v[80:95], v[184:187], v[100:103], v[80:95]
	s_waitcnt lgkmcnt(5)
	v_mfma_f32_32x32x16_bf16 v[80:95], v[188:191], v[104:107], v[80:95]
	s_waitcnt lgkmcnt(4)
	v_mfma_f32_32x32x16_bf16 v[80:95], v[192:195], v[108:111], v[80:95]
	s_waitcnt lgkmcnt(3)
	v_mfma_f32_32x32x16_bf16 v[64:79], v[196:199], v[96:99], v[48:63]
	s_waitcnt lgkmcnt(2)
	v_mfma_f32_32x32x16_bf16 v[64:79], v[200:203], v[100:103], v[64:79]
	s_waitcnt lgkmcnt(1)
	v_mfma_f32_32x32x16_bf16 v[64:79], v[204:207], v[104:107], v[64:79]
	s_waitcnt lgkmcnt(0)
	v_mfma_f32_32x32x16_bf16 v[64:79], v[226:229], v[108:111], v[64:79]
	s_nop 1
	s_cbranch_scc1 .LBB0_872
	v_add_u32_e32 v0, s72, v148
	v_sub_u32_e32 v2, v119, v0
	v_sub_u32_e32 v0, v170, v0
	v_add_u32_e32 v3, s69, v148
	v_cmp_lt_i32_e32 vcc, 0, v2
	v_cmp_gt_i32_e64 s[0:1], 0, v0
	v_sub_u32_e32 v4, v119, v3
	v_sub_u32_e32 v3, v170, v3
	s_or_b64 vcc, vcc, s[0:1]
	v_cndmask_b32_e32 v80, v80, v217, vcc
	v_cmp_lt_i32_e32 vcc, 0, v4
	v_cmp_gt_i32_e64 s[0:1], 0, v3
	s_or_b64 vcc, vcc, s[0:1]
	v_cndmask_b32_e32 v64, v64, v217, vcc
	v_cmp_lt_i32_e32 vcc, 1, v2
	v_cmp_gt_i32_e64 s[0:1], 1, v0
	s_or_b64 vcc, vcc, s[0:1]
	v_cndmask_b32_e32 v81, v81, v217, vcc
	v_cmp_lt_i32_e32 vcc, 1, v4
	v_cmp_gt_i32_e64 s[0:1], 1, v3
	s_or_b64 vcc, vcc, s[0:1]
	v_cndmask_b32_e32 v65, v65, v217, vcc
	v_cmp_lt_i32_e32 vcc, 2, v2
	v_cmp_gt_i32_e64 s[0:1], 2, v0
	s_or_b64 vcc, vcc, s[0:1]
	v_cndmask_b32_e32 v82, v82, v217, vcc
	v_cmp_lt_i32_e32 vcc, 2, v4
	v_cmp_gt_i32_e64 s[0:1], 2, v3
	s_or_b64 vcc, vcc, s[0:1]
	v_cndmask_b32_e32 v66, v66, v217, vcc
	v_cmp_lt_i32_e32 vcc, 3, v2
	v_cmp_gt_i32_e64 s[0:1], 3, v0
	s_or_b64 vcc, vcc, s[0:1]
	v_cndmask_b32_e32 v83, v83, v217, vcc
	v_cmp_lt_i32_e32 vcc, 3, v4
	v_cmp_gt_i32_e64 s[0:1], 3, v3
	s_or_b64 vcc, vcc, s[0:1]
	v_cndmask_b32_e32 v67, v67, v217, vcc
	v_cmp_lt_i32_e32 vcc, 8, v2
	v_cmp_gt_i32_e64 s[0:1], 8, v0
	s_or_b64 vcc, vcc, s[0:1]
	v_cndmask_b32_e32 v84, v84, v217, vcc
	v_cmp_lt_i32_e32 vcc, 8, v4
	v_cmp_gt_i32_e64 s[0:1], 8, v3
	s_or_b64 vcc, vcc, s[0:1]
	v_cndmask_b32_e32 v68, v68, v217, vcc
	v_cmp_lt_i32_e32 vcc, 9, v2
	v_cmp_gt_i32_e64 s[0:1], 9, v0
	s_or_b64 vcc, vcc, s[0:1]
	v_cndmask_b32_e32 v85, v85, v217, vcc
	v_cmp_lt_i32_e32 vcc, 9, v4
	v_cmp_gt_i32_e64 s[0:1], 9, v3
	s_or_b64 vcc, vcc, s[0:1]
	v_cndmask_b32_e32 v69, v69, v217, vcc
	v_cmp_lt_i32_e32 vcc, 10, v2
	v_cmp_gt_i32_e64 s[0:1], 10, v0
	s_or_b64 vcc, vcc, s[0:1]
	v_cndmask_b32_e32 v86, v86, v217, vcc
	v_cmp_lt_i32_e32 vcc, 10, v4
	v_cmp_gt_i32_e64 s[0:1], 10, v3
	s_or_b64 vcc, vcc, s[0:1]
	v_cndmask_b32_e32 v70, v70, v217, vcc
	v_cmp_lt_i32_e32 vcc, 11, v2
	v_cmp_gt_i32_e64 s[0:1], 11, v0
	s_or_b64 vcc, vcc, s[0:1]
	v_cndmask_b32_e32 v87, v87, v217, vcc
	v_cmp_lt_i32_e32 vcc, 11, v4
	v_cmp_gt_i32_e64 s[0:1], 11, v3
	s_or_b64 vcc, vcc, s[0:1]
	v_cndmask_b32_e32 v71, v71, v217, vcc
	v_cmp_lt_i32_e32 vcc, 16, v2
	v_cmp_gt_i32_e64 s[0:1], 16, v0
	s_or_b64 vcc, vcc, s[0:1]
	v_cndmask_b32_e32 v88, v88, v217, vcc
	v_cmp_lt_i32_e32 vcc, 16, v4
	v_cmp_gt_i32_e64 s[0:1], 16, v3
	s_or_b64 vcc, vcc, s[0:1]
	v_cndmask_b32_e32 v72, v72, v217, vcc
	v_cmp_lt_i32_e32 vcc, 17, v2
	v_cmp_gt_i32_e64 s[0:1], 17, v0
	s_or_b64 vcc, vcc, s[0:1]
	v_cndmask_b32_e32 v89, v89, v217, vcc
	v_cmp_lt_i32_e32 vcc, 17, v4
	v_cmp_gt_i32_e64 s[0:1], 17, v3
	s_or_b64 vcc, vcc, s[0:1]
	v_cndmask_b32_e32 v73, v73, v217, vcc
	v_cmp_lt_i32_e32 vcc, 18, v2
	v_cmp_gt_i32_e64 s[0:1], 18, v0
	s_or_b64 vcc, vcc, s[0:1]
	v_cndmask_b32_e32 v90, v90, v217, vcc
	v_cmp_lt_i32_e32 vcc, 18, v4
	v_cmp_gt_i32_e64 s[0:1], 18, v3
	s_or_b64 vcc, vcc, s[0:1]
	v_cndmask_b32_e32 v74, v74, v217, vcc
	v_cmp_lt_i32_e32 vcc, 19, v2
	v_cmp_gt_i32_e64 s[0:1], 19, v0
	s_or_b64 vcc, vcc, s[0:1]
	v_cndmask_b32_e32 v91, v91, v217, vcc
	v_cmp_lt_i32_e32 vcc, 19, v4
	v_cmp_gt_i32_e64 s[0:1], 19, v3
	s_or_b64 vcc, vcc, s[0:1]
	v_cndmask_b32_e32 v75, v75, v217, vcc
	v_cmp_lt_i32_e32 vcc, 24, v2
	v_cmp_gt_i32_e64 s[0:1], 24, v0
	s_or_b64 vcc, vcc, s[0:1]
	v_cndmask_b32_e32 v92, v92, v217, vcc
	v_cmp_lt_i32_e32 vcc, 24, v4
	v_cmp_gt_i32_e64 s[0:1], 24, v3
	s_or_b64 vcc, vcc, s[0:1]
	v_cndmask_b32_e32 v76, v76, v217, vcc
	v_cmp_lt_i32_e32 vcc, 25, v2
	v_cmp_gt_i32_e64 s[0:1], 25, v0
	s_or_b64 vcc, vcc, s[0:1]
	v_cndmask_b32_e32 v93, v93, v217, vcc
	v_cmp_lt_i32_e32 vcc, 25, v4
	v_cmp_gt_i32_e64 s[0:1], 25, v3
	s_or_b64 vcc, vcc, s[0:1]
	v_cndmask_b32_e32 v77, v77, v217, vcc
	v_cmp_lt_i32_e32 vcc, 26, v2
	v_cmp_gt_i32_e64 s[0:1], 26, v0
	s_or_b64 vcc, vcc, s[0:1]
	v_cndmask_b32_e32 v94, v94, v217, vcc
	v_cmp_lt_i32_e32 vcc, 26, v4
	v_cmp_gt_i32_e64 s[0:1], 26, v3
	s_or_b64 vcc, vcc, s[0:1]
	v_cndmask_b32_e32 v78, v78, v217, vcc
	v_cmp_lt_i32_e32 vcc, 27, v2
	v_cmp_gt_i32_e64 s[0:1], 27, v0
	s_or_b64 vcc, vcc, s[0:1]
	v_cndmask_b32_e32 v95, v95, v217, vcc
	v_cmp_lt_i32_e32 vcc, 27, v4
	v_cmp_gt_i32_e64 s[0:1], 27, v3
	s_or_b64 vcc, vcc, s[0:1]
	v_cndmask_b32_e32 v79, v79, v217, vcc
; #define LAS3 __attribute__((address_space(3)))
; DI unsigned pk2(float lo, float hi) { f32x2 v = {lo, hi}; return __builtin_bit_cast(unsigned, __builtin_convertvector(v, bf16x2v)); }
; DI void pv_tile(LAS3 const char* vb, const AttnLane& L, const f32x16& pr, f32x16& o0, f32x16& o1) {
;   u32x4 w0, w1;
;   w0[0] = pk2(pr[0], pr[1]); w0[1] = pk2(pr[2], pr[3]); w0[2] = pk2(pr[4], pr[5]); w0[3] = pk2(pr[6], pr[7]);
;   w1[0] = pk2(pr[8], pr[9]); w1[1] = pk2(pr[10], pr[11]); w1[2] = pk2(pr[12], pr[13]); w1[3] = pk2(pr[14], pr[15]);
;   const bf16x8 pf0 = __builtin_bit_cast(bf16x8, w0), pf1 = __builtin_bit_cast(bf16x8, w1);
;   o0 = __builtin_amdgcn_mfma_f32_32x32x16_bf16(tr_pair(vb + L.vr00, vb + L.vr01), pf0, o0, 0, 0, 0);
;   o1 = __builtin_amdgcn_mfma_f32_32x32x16_bf16(tr_pair(vb + L.vr10, vb + L.vr11), pf0, o1, 0, 0, 0);
;   o0 = __builtin_amdgcn_mfma_f32_32x32x16_bf16(tr_pair(vb + 2048 + L.vr00, vb + 2048 + L.vr01), pf1, o0, 0, 0, 0);
;   o1 = __builtin_amdgcn_mfma_f32_32x32x16_bf16(tr_pair(vb + 2048 + L.vr10, vb + 2048 + L.vr11), pf1, o1, 0, 0, 0);
; }
; template <int MK> ...
;     ...
; #pragma unroll
;   for (int v = 0; v < 16; ++v) s0[v] = __builtin_amdgcn_exp2f(s0[v]);
;   const float a0 = (s0[0] + s0[1]) + (s0[2] + s0[3]), a1 = (s0[4] + s0[5]) + (s0[6] + s0[7]);
;   const float a2 = (s0[8] + s0[9]) + (s0[10] + s0[11]), a3 = (s0[12] + s0[13]) + (s0[14] + s0[15]);
;   pv_tile(v0, L, s0, st.o0, st.o1);
; #pragma unroll
;   for (int v = 0; v < 16; ++v) s1[v] = __builtin_amdgcn_exp2f(s1[v]);
;   const float a4 = (s1[0] + s1[1]) + (s1[2] + s1[3]), a5 = (s1[4] + s1[5]) + (s1[6] + s1[7]);
;   const float a6 = (s1[8] + s1[9]) + (s1[10] + s1[11]), a7 = (s1[12] + s1[13]) + (s1[14] + s1[15]);
;   pv_tile(v1, L, s1, st.o0, st.o1);
;   const float sum = ((a0 + a1) + (a2 + a3)) + ((a4 + a5) + (a6 + a7));
;   st.l += sum;
;   const float tot = sum + __shfl_xor(sum, 32);
;   if (__builtin_amdgcn_ballot_w64(tot > 256.f) != 0) {
;     const float delta = fmaxf(__builtin_amdgcn_logf(tot), 0.f);
;     const float alpha = __builtin_amdgcn_exp2f(-delta);
;     st.m += delta; st.l *= alpha;
; #pragma unroll
;     for (int v = 0; v < 16; ++v) { st.cinit[v] -= delta; st.o0[v] *= alpha; st.o1[v] *= alpha; }
;   }
.LBB0_872:
	v_add_u32_e32 v0, s33, v149
	v_exp_f32_e32 v125, v80
	v_exp_f32_e32 v129, v81
	v_exp_f32_e32 v127, v82
	v_exp_f32_e32 v131, v83
	v_exp_f32_e32 v83, v84
	v_exp_f32_e32 v123, v85
	v_exp_f32_e32 v85, v86
	v_exp_f32_e32 v87, v87
	v_exp_f32_e32 v3, v88
	v_exp_f32_e32 v7, v89
	v_exp_f32_e32 v5, v90
	v_exp_f32_e32 v11, v91
	v_add_u32_e32 v180, s33, v150
	s_nop 0
	ds_read_b64_tr_b16 v[88:89], v0 offset:16384
	ds_read_b64_tr_b16 v[90:91], v180 offset:16384
	v_add_u32_e32 v181, s33, v151
	v_exp_f32_e32 v124, v64
	v_exp_f32_e32 v128, v65
	v_exp_f32_e32 v126, v66
	v_exp_f32_e32 v130, v67
	v_cvt_pk_bf16_f32 v64, v125, v129
	v_cvt_pk_bf16_f32 v65, v127, v131
	v_cvt_pk_bf16_f32 v66, v83, v123
	v_cvt_pk_bf16_f32 v67, v85, v87
	v_exp_f32_e32 v9, v92
	v_exp_f32_e32 v15, v93
	v_exp_f32_e32 v13, v94
	v_exp_f32_e32 v81, v95
	v_add_u32_e32 v182, s33, v152
	ds_read_b64_tr_b16 v[92:93], v181 offset:16384
	ds_read_b64_tr_b16 v[94:95], v182 offset:16384
	ds_read_b64_tr_b16 v[172:173], v0 offset:18432
	ds_read_b64_tr_b16 v[174:175], v180 offset:18432
	ds_read_b64_tr_b16 v[176:177], v181 offset:18432
	ds_read_b64_tr_b16 v[178:179], v182 offset:18432
	s_waitcnt lgkmcnt(6)
	v_mfma_f32_32x32x16_bf16 v[32:47], v[88:91], v[64:67], v[32:47]
	v_exp_f32_e32 v82, v68
	v_exp_f32_e32 v122, v69
	v_exp_f32_e32 v84, v70
	v_exp_f32_e32 v86, v71
	v_exp_f32_e32 v2, v72
	v_exp_f32_e32 v6, v73
	v_exp_f32_e32 v4, v74
	s_waitcnt lgkmcnt(4)
	v_mfma_f32_32x32x16_bf16 v[16:31], v[92:95], v[64:67], v[16:31]
	v_cvt_pk_bf16_f32 v64, v3, v7
	v_cvt_pk_bf16_f32 v65, v5, v11
	v_cvt_pk_bf16_f32 v66, v9, v15
	v_cvt_pk_bf16_f32 v67, v13, v81
	v_exp_f32_e32 v10, v75
	v_exp_f32_e32 v8, v76
	v_exp_f32_e32 v14, v77
	s_waitcnt lgkmcnt(2)
	v_mfma_f32_32x32x16_bf16 v[32:47], v[172:175], v[64:67], v[32:47]
	v_exp_f32_e32 v12, v78
	v_exp_f32_e32 v80, v79
	ds_read_b64_tr_b16 v[68:69], v0 offset:20480
	ds_read_b64_tr_b16 v[70:71], v180 offset:20480
	ds_read_b64_tr_b16 v[72:73], v181 offset:20480
	ds_read_b64_tr_b16 v[74:75], v182 offset:20480
	ds_read_b64_tr_b16 v[76:77], v0 offset:22528
	ds_read_b64_tr_b16 v[78:79], v180 offset:22528
	ds_read_b64_tr_b16 v[88:89], v181 offset:22528
	ds_read_b64_tr_b16 v[90:91], v182 offset:22528
	v_add_f32_e32 v92, v124, v128
	v_add_f32_e32 v93, v125, v129
	v_add_f32_e32 v94, v126, v130
	v_add_f32_e32 v95, v127, v131
	s_waitcnt lgkmcnt(8)
	v_mfma_f32_32x32x16_bf16 v[16:31], v[176:179], v[64:67], v[16:31]
	v_cvt_pk_bf16_f32 v64, v124, v128
	v_cvt_pk_bf16_f32 v65, v126, v130
	v_cvt_pk_bf16_f32 v66, v82, v122
	v_cvt_pk_bf16_f32 v67, v84, v86
	s_waitcnt lgkmcnt(6)
	s_nop 0
	v_mfma_f32_32x32x16_bf16 v[32:47], v[68:71], v[64:67], v[32:47]
	v_add_f32_e64 v70, v82, v122
	v_add_f32_e64 v71, v83, v123
	v_add_f32_e64 v82, v84, v86
	v_add_f32_e64 v83, v85, v87
	v_add_f32_e64 v84, v4, v10
	v_add_f32_e64 v85, v5, v11
	v_add_f32_e32 v70, v70, v82
	v_add_f32_e32 v71, v71, v83
	v_add_f32_e32 v82, v2, v6
	v_add_f32_e32 v83, v3, v7
	v_add_f32_e32 v68, v92, v94
	v_add_f32_e32 v69, v93, v95
	v_add_f32_e32 v82, v82, v84
	v_add_f32_e32 v83, v83, v85
	s_waitcnt lgkmcnt(4)
	v_mfma_f32_32x32x16_bf16 v[16:31], v[72:75], v[64:67], v[16:31]
	v_add_f32_e64 v64, v8, v14
	v_add_f32_e64 v65, v9, v15
	v_add_f32_e64 v66, v12, v80
	v_add_f32_e64 v67, v13, v81
	v_cvt_pk_bf16_f32 v2, v2, v6
	v_add_f32_e32 v64, v64, v66
	v_add_f32_e32 v65, v65, v67
	v_cvt_pk_bf16_f32 v3, v4, v10
	v_cvt_pk_bf16_f32 v4, v8, v14
	v_add_f32_e32 v6, v68, v70
	v_add_f32_e32 v7, v69, v71
	v_add_f32_e32 v8, v82, v64
	v_add_f32_e32 v9, v83, v65
	v_cvt_pk_bf16_f32 v5, v12, v80
	v_add_f32_e32 v6, v6, v8
	v_add_f32_e32 v7, v7, v9
	s_nop 0
	v_add_f32_e32 v0, v6, v7
	v_and_b32_e32 v7, 64, v214
	v_xor_b32_e32 v6, 32, v214
	v_add_u32_e32 v7, 64, v7
	v_cmp_lt_i32_e32 vcc, v6, v7
	s_waitcnt lgkmcnt(2)
	v_mfma_f32_32x32x16_bf16 v[32:47], v[76:79], v[2:5], v[32:47]
	v_add_f32_e32 v171, v171, v0
	v_cndmask_b32_e32 v6, v214, v6, vcc
	v_lshlrev_b32_e32 v6, 2, v6
	ds_bpermute_b32 v6, v6, v0
	s_waitcnt lgkmcnt(0)
	v_add_f32_e32 v0, v0, v6
	v_mfma_f32_32x32x16_bf16 v[16:31], v[88:91], v[2:5], v[16:31]
	v_cmp_lt_f32_e32 vcc, s68, v0
	s_cbranch_vccz .LBB0_865
	v_log_f32_e32 v0, v0
	s_nop 0
	v_max_f32_e32 v2, 0, v0
	v_exp_f32_e64 v0, -v2
	v_add_f32_e32 v117, v117, v2
	v_sub_f32_e32 v63, v63, v2
	v_sub_f32_e32 v62, v62, v2
	v_sub_f32_e32 v61, v61, v2
	v_sub_f32_e32 v60, v60, v2
	v_sub_f32_e32 v59, v59, v2
	v_mul_f32_e32 v171, v171, v0
	v_sub_f32_e32 v58, v58, v2
	v_sub_f32_e32 v57, v57, v2
	v_sub_f32_e32 v56, v56, v2
	v_sub_f32_e32 v55, v55, v2
	v_sub_f32_e32 v54, v54, v2
	v_sub_f32_e32 v53, v53, v2
	v_sub_f32_e32 v52, v52, v2
	v_sub_f32_e32 v51, v51, v2
	v_sub_f32_e32 v50, v50, v2
	v_sub_f32_e32 v49, v49, v2
	v_sub_f32_e32 v48, v48, v2
	v_pk_mul_f32 v[46:47], v[46:47], v[0:1] op_sel_hi:[1,0]
	v_pk_mul_f32 v[44:45], v[44:45], v[0:1] op_sel_hi:[1,0]
	v_pk_mul_f32 v[42:43], v[42:43], v[0:1] op_sel_hi:[1,0]
	v_pk_mul_f32 v[40:41], v[40:41], v[0:1] op_sel_hi:[1,0]
	v_pk_mul_f32 v[38:39], v[38:39], v[0:1] op_sel_hi:[1,0]
	v_pk_mul_f32 v[36:37], v[36:37], v[0:1] op_sel_hi:[1,0]
	v_pk_mul_f32 v[34:35], v[34:35], v[0:1] op_sel_hi:[1,0]
	v_pk_mul_f32 v[32:33], v[32:33], v[0:1] op_sel_hi:[1,0]
	v_pk_mul_f32 v[30:31], v[30:31], v[0:1] op_sel_hi:[1,0]
	v_pk_mul_f32 v[28:29], v[28:29], v[0:1] op_sel_hi:[1,0]
	v_pk_mul_f32 v[26:27], v[26:27], v[0:1] op_sel_hi:[1,0]
	v_pk_mul_f32 v[24:25], v[24:25], v[0:1] op_sel_hi:[1,0]
	v_pk_mul_f32 v[22:23], v[22:23], v[0:1] op_sel_hi:[1,0]
	v_pk_mul_f32 v[20:21], v[20:21], v[0:1] op_sel_hi:[1,0]
	v_pk_mul_f32 v[18:19], v[18:19], v[0:1] op_sel_hi:[1,0]
	v_pk_mul_f32 v[16:17], v[16:17], v[0:1] op_sel_hi:[1,0]
	s_branch .LBB0_865

; template <int MK> ...
;   f32x16 s0 = qk_tile(k0, L, q0, q1, q2, q3, init);
;   f32x16 s1 = qk_tile(k1, L, q0, q1, q2, q3, init);
;   if (MK == 2) {
; #pragma unroll
;     for (int v = 0; v < 16; ++v) { s0[v] += b0[(v & 3) + 8 * (v >> 2)]; s1[v] += b1[(v & 3) + 8 * (v >> 2)]; }
;   }
;   if (MK == 1 && kb1 != 0x7fffffff) {
;     const int lo = max(0, sq - 128), hi = min(2047, sq + 128);
;     const int L0 = lo - kb0 - 4 * h, H0 = hi - kb0 - 4 * h, L1 = lo - kb1 - 4 * h, H1 = hi - kb1 - 4 * h;
; #pragma unroll
;     for (int v = 0; v < 16; ++v) {
;       const int cv = (v & 3) + 8 * (v >> 2);
;       s0[v] = (cv >= L0 && cv <= H0) ? s0[v] : -1e30f;
;       s1[v] = (cv >= L1 && cv <= H1) ? s1[v] : -1e30f;
;     }
;   }
; #pragma unroll
;   for (int v = 0; v < 16; ++v) s0[v] = __builtin_amdgcn_exp2f(s0[v]);
;   const float a0 = (s0[0] + s0[1]) + (s0[2] + s0[3]), a1 = (s0[4] + s0[5]) + (s0[6] + s0[7]);
;   const float a2 = (s0[8] + s0[9]) + (s0[10] + s0[11]), a3 = (s0[12] + s0[13]) + (s0[14] + s0[15]);
;   pv_tile(v0, L, s0, st.o0, st.o1);
; #pragma unroll
;   for (int v = 0; v < 16; ++v) s1[v] = __builtin_amdgcn_exp2f(s1[v]);
;   const float a4 = (s1[0] + s1[1]) + (s1[2] + s1[3]), a5 = (s1[4] + s1[5]) + (s1[6] + s1[7]);
;   const float a6 = (s1[8] + s1[9]) + (s1[10] + s1[11]), a7 = (s1[12] + s1[13]) + (s1[14] + s1[15]);
;   pv_tile(v1, L, s1, st.o0, st.o1);
;   const float sum = ((a0 + a1) + (a2 + a3)) + ((a4 + a5) + (a6 + a7));
;   st.l += sum;
;   const float tot = sum + __shfl_xor(sum, 32);
;   if (__builtin_amdgcn_ballot_w64(tot > 256.f) != 0) {
;     const float delta = fmaxf(__builtin_amdgcn_logf(tot), 0.f);
;     const float alpha = __builtin_amdgcn_exp2f(-delta);
;     st.m += delta; st.l *= alpha;
; #pragma unroll
;     for (int v = 0; v < 16; ++v) { st.cinit[v] -= delta; st.o0[v] *= alpha; st.o1[v] *= alpha; }
;   }
.LBB0_899:
	s_add_i32 s23, s22, s23
	v_add_u32_e32 v54, s23, v129
	ds_read_b128 v[50:53], v54
	ds_read_b128 v[106:109], v54 offset:4096
	v_add_u32_e32 v110, s23, v130
	v_add_u32_e32 v111, s23, v131
	v_add_u32_e32 v112, s23, v132
	v_add_u32_e32 v176, s23, v133
	v_add_u32_e32 v177, s23, v134
	v_add_u32_e32 v178, s23, v135
	v_add_u32_e32 v179, s23, v136
	s_waitcnt lgkmcnt(0)
	v_mfma_f32_32x32x16_bf16 v[66:81], v[50:53], v[82:85], v[34:49]
	ds_read_b128 v[50:53], v110
	s_waitcnt lgkmcnt(0)
	v_mfma_f32_32x32x16_bf16 v[66:81], v[50:53], v[86:89], v[66:81]
	ds_read_b128 v[50:53], v111
	s_waitcnt lgkmcnt(0)
	v_mfma_f32_32x32x16_bf16 v[66:81], v[50:53], v[90:93], v[66:81]
	v_mfma_f32_32x32x16_bf16 v[50:65], v[106:109], v[82:85], v[34:49]
	ds_read_b128 v[106:109], v112
	ds_read_b128 v[160:163], v110 offset:4096
	ds_read_b128 v[164:167], v111 offset:4096
	ds_read_b128 v[168:171], v112 offset:4096
	s_waitcnt lgkmcnt(0)
	v_mfma_f32_32x32x16_bf16 v[50:65], v[160:163], v[86:89], v[50:65]
	s_nop 0
	ds_read_b64_tr_b16 v[160:161], v176 offset:16384
	ds_read_b64_tr_b16 v[162:163], v177 offset:16384
	v_mfma_f32_32x32x16_bf16 v[50:65], v[164:167], v[90:93], v[50:65]
	v_mfma_f32_32x32x16_bf16 v[66:81], v[106:109], v[94:97], v[66:81]
	v_mfma_f32_32x32x16_bf16 v[50:65], v[168:171], v[94:97], v[50:65]
	s_nop 10
	v_exp_f32_e32 v116, v66
	v_exp_f32_e32 v120, v67
	v_exp_f32_e32 v118, v68
	v_exp_f32_e32 v124, v69
	v_exp_f32_e32 v108, v70
	v_exp_f32_e32 v112, v71
	v_exp_f32_e32 v110, v72
	v_exp_f32_e32 v114, v73
	ds_read_b64_tr_b16 v[164:165], v178 offset:16384
	ds_read_b64_tr_b16 v[166:167], v179 offset:16384
	ds_read_b64_tr_b16 v[172:173], v176 offset:18432
	ds_read_b64_tr_b16 v[174:175], v177 offset:18432
	ds_read_b64_tr_b16 v[66:67], v178 offset:18432
	ds_read_b64_tr_b16 v[68:69], v179 offset:18432
	v_exp_f32_e32 v117, v50
	v_exp_f32_e32 v121, v51
	v_exp_f32_e32 v119, v52
	v_exp_f32_e32 v125, v53
	v_cvt_pk_bf16_f32 v50, v116, v120
	v_cvt_pk_bf16_f32 v51, v118, v124
	v_cvt_pk_bf16_f32 v52, v108, v112
	v_cvt_pk_bf16_f32 v53, v110, v114
	v_exp_f32_e32 v70, v74
	v_exp_f32_e32 v74, v75
	s_waitcnt lgkmcnt(6)
	v_mfma_f32_32x32x16_bf16 v[18:33], v[160:163], v[50:53], v[18:33]
	v_exp_f32_e32 v72, v76
	v_exp_f32_e32 v106, v77
	v_exp_f32_e32 v76, v78
	v_exp_f32_e32 v78, v79
	v_exp_f32_e32 v80, v80
	v_exp_f32_e32 v122, v81
	v_exp_f32_e32 v109, v54
	s_waitcnt lgkmcnt(4)
	v_mfma_f32_32x32x16_bf16 v[2:17], v[164:167], v[50:53], v[2:17]
	v_exp_f32_e32 v113, v55
	v_exp_f32_e32 v111, v56
	v_exp_f32_e32 v115, v57
	ds_read_b64_tr_b16 v[50:51], v176 offset:20480
	v_cvt_pk_bf16_f32 v54, v70, v74
	v_cvt_pk_bf16_f32 v55, v72, v106
	v_cvt_pk_bf16_f32 v56, v76, v78
	v_cvt_pk_bf16_f32 v57, v80, v122
	v_exp_f32_e32 v71, v58
	v_exp_f32_e32 v75, v59
	s_waitcnt lgkmcnt(3)
	v_mfma_f32_32x32x16_bf16 v[18:33], v[172:175], v[54:57], v[18:33]
	v_exp_f32_e32 v73, v60
	v_exp_f32_e32 v107, v61
	v_exp_f32_e32 v77, v62
	v_exp_f32_e32 v79, v63
	v_exp_f32_e32 v81, v64
	v_exp_f32_e32 v123, v65
	ds_read_b64_tr_b16 v[52:53], v177 offset:20480
	ds_read_b64_tr_b16 v[58:59], v178 offset:20480
	ds_read_b64_tr_b16 v[60:61], v179 offset:20480
	ds_read_b64_tr_b16 v[62:63], v176 offset:22528
	ds_read_b64_tr_b16 v[64:65], v177 offset:22528
	ds_read_b64_tr_b16 v[160:161], v178 offset:22528
	ds_read_b64_tr_b16 v[162:163], v179 offset:22528
	s_waitcnt lgkmcnt(8)
	v_mfma_f32_32x32x16_bf16 v[2:17], v[66:69], v[54:57], v[2:17]
	v_add_f32_e64 v54, v116, v120
	v_add_f32_e64 v55, v117, v121
	v_add_f32_e64 v56, v118, v124
	v_add_f32_e64 v57, v119, v125
	v_add_f32_e64 v68, v72, v106
	v_add_f32_e64 v69, v73, v107
	v_add_f32_e32 v66, v54, v56
	v_add_f32_e32 v67, v55, v57
	v_cvt_pk_bf16_f32 v54, v117, v121
	v_cvt_pk_bf16_f32 v55, v119, v125
	v_cvt_pk_bf16_f32 v56, v109, v113
	v_cvt_pk_bf16_f32 v57, v111, v115
	s_waitcnt lgkmcnt(6)
	s_nop 0
	v_mfma_f32_32x32x16_bf16 v[18:33], v[50:53], v[54:57], v[18:33]
	v_add_f32_e64 v50, v108, v112
	v_add_f32_e64 v51, v109, v113
	v_add_f32_e64 v52, v110, v114
	v_add_f32_e64 v53, v111, v115
	v_add_f32_e64 v50, v50, v52
	v_add_f32_e64 v51, v51, v53
	v_add_f32_e32 v52, v70, v74
	v_add_f32_e32 v53, v71, v75
	v_add_f32_e32 v50, v66, v50
	v_add_f32_e32 v51, v67, v51
	v_add_f32_e32 v68, v52, v68
	v_add_f32_e32 v69, v53, v69
	s_waitcnt lgkmcnt(4)
	v_mfma_f32_32x32x16_bf16 v[2:17], v[58:61], v[54:57], v[2:17]
	v_add_f32_e64 v52, v76, v78
	v_add_f32_e64 v53, v77, v79
	v_add_f32_e64 v54, v80, v122
	v_add_f32_e64 v55, v81, v123
	v_add_f32_e64 v56, v52, v54
	v_add_f32_e64 v57, v53, v55
	v_cvt_pk_bf16_f32 v52, v71, v75
	v_add_f32_e32 v56, v68, v56
	v_add_f32_e32 v57, v69, v57
	v_cvt_pk_bf16_f32 v53, v73, v107
	v_cvt_pk_bf16_f32 v54, v77, v79
	v_cvt_pk_bf16_f32 v55, v81, v123
	v_add_f32_e32 v50, v50, v56
	v_add_f32_e32 v51, v51, v57
	s_waitcnt lgkmcnt(2)
	v_mfma_f32_32x32x16_bf16 v[18:33], v[62:65], v[52:55], v[18:33]
	v_add_f32_e32 v50, v50, v51
	ds_bpermute_b32 v51, v159, v50
	v_add_f32_e32 v103, v103, v50
	s_waitcnt lgkmcnt(0)
	v_add_f32_e32 v50, v50, v51
	v_mfma_f32_32x32x16_bf16 v[2:17], v[160:163], v[52:55], v[2:17]
	v_cmp_lt_f32_e32 vcc, s68, v50
	s_cbranch_vccz .LBB0_898
	v_log_f32_e32 v50, v50
	s_nop 0
	v_max_f32_e32 v51, 0, v50
	v_exp_f32_e64 v50, -v51
	v_add_f32_e32 v101, v101, v51
	v_sub_f32_e32 v49, v49, v51
	v_sub_f32_e32 v48, v48, v51
	v_sub_f32_e32 v47, v47, v51
	v_sub_f32_e32 v46, v46, v51
	v_sub_f32_e32 v45, v45, v51
	v_mul_f32_e32 v103, v103, v50
	v_sub_f32_e32 v44, v44, v51
	v_sub_f32_e32 v43, v43, v51
	v_sub_f32_e32 v42, v42, v51
	v_sub_f32_e32 v41, v41, v51
	v_sub_f32_e32 v40, v40, v51
	v_sub_f32_e32 v39, v39, v51
	v_sub_f32_e32 v38, v38, v51
	v_sub_f32_e32 v37, v37, v51
	v_sub_f32_e32 v36, v36, v51
	v_sub_f32_e32 v35, v35, v51
	v_sub_f32_e32 v34, v34, v51
	v_pk_mul_f32 v[32:33], v[32:33], v[50:51] op_sel_hi:[1,0]
	v_pk_mul_f32 v[30:31], v[30:31], v[50:51] op_sel_hi:[1,0]
	v_pk_mul_f32 v[28:29], v[28:29], v[50:51] op_sel_hi:[1,0]
	v_pk_mul_f32 v[26:27], v[26:27], v[50:51] op_sel_hi:[1,0]
	v_pk_mul_f32 v[24:25], v[24:25], v[50:51] op_sel_hi:[1,0]
	v_pk_mul_f32 v[22:23], v[22:23], v[50:51] op_sel_hi:[1,0]
	v_pk_mul_f32 v[20:21], v[20:21], v[50:51] op_sel_hi:[1,0]
	v_pk_mul_f32 v[18:19], v[18:19], v[50:51] op_sel_hi:[1,0]
	v_pk_mul_f32 v[16:17], v[16:17], v[50:51] op_sel_hi:[1,0]
	v_pk_mul_f32 v[14:15], v[14:15], v[50:51] op_sel_hi:[1,0]
	v_pk_mul_f32 v[12:13], v[12:13], v[50:51] op_sel_hi:[1,0]
	v_pk_mul_f32 v[10:11], v[10:11], v[50:51] op_sel_hi:[1,0]
	v_pk_mul_f32 v[8:9], v[8:9], v[50:51] op_sel_hi:[1,0]
	v_pk_mul_f32 v[6:7], v[6:7], v[50:51] op_sel_hi:[1,0]
	v_pk_mul_f32 v[4:5], v[4:5], v[50:51] op_sel_hi:[1,0]
	v_pk_mul_f32 v[2:3], v[2:3], v[50:51] op_sel_hi:[1,0]
	s_branch .LBB0_898

; __global__ void __launch_bounds__(512, 2) mega(Params p, int ph_lo, int ph_hi) {
;   extern __shared__ __attribute__((aligned(16))) char smem[];
	.amdhsa_kernel _Z4mega6Paramsii
		.amdhsa_group_segment_fixed_size 0
		.amdhsa_private_segment_fixed_size 0
		.amdhsa_kernarg_size 472
		.amdhsa_user_sgpr_count 2
		.amdhsa_user_sgpr_dispatch_ptr 0
		.amdhsa_user_sgpr_queue_ptr 0
		.amdhsa_user_sgpr_kernarg_segment_ptr 1
		.amdhsa_user_sgpr_dispatch_id 0
		.amdhsa_user_sgpr_kernarg_preload_length 0
		.amdhsa_user_sgpr_kernarg_preload_offset 0
		.amdhsa_user_sgpr_private_segment_size 0
		.amdhsa_uses_dynamic_stack 0
		.amdhsa_enable_private_segment 0
		.amdhsa_system_sgpr_workgroup_id_x 1
		.amdhsa_system_sgpr_workgroup_id_y 0
		.amdhsa_system_sgpr_workgroup_id_z 0
		.amdhsa_system_sgpr_workgroup_info 0
		.amdhsa_system_vgpr_workitem_id 2
		.amdhsa_next_free_vgpr 256
		.amdhsa_next_free_sgpr 102
		.amdhsa_accum_offset 256
		.amdhsa_reserve_vcc 1
		.amdhsa_float_round_mode_32 0
		.amdhsa_float_round_mode_16_64 0
		.amdhsa_float_denorm_mode_32 3
		.amdhsa_float_denorm_mode_16_64 3
		.amdhsa_dx10_clamp 1
		.amdhsa_ieee_mode 1
		.amdhsa_fp16_overflow 0
		.amdhsa_tg_split 0
		.amdhsa_exception_fp_ieee_invalid_op 0
		.amdhsa_exception_fp_denorm_src 0
		.amdhsa_exception_fp_ieee_div_zero 0
		.amdhsa_exception_fp_ieee_overflow 0
		.amdhsa_exception_fp_ieee_underflow 0
		.amdhsa_exception_fp_ieee_inexact 0
		.amdhsa_exception_int_div_zero 0
	.end_amdhsa_kernel

; __global__ void __launch_bounds__(512, 2) mega(Params p, int ph_lo, int ph_hi) {
amdhsa.kernels:
  - .agpr_count:     0
    .args:
      - .offset:         0
        .size:           208
        .value_kind:     by_value
      - .offset:         208
        .size:           4
        .value_kind:     by_value
      - .offset:         212
        .size:           4
        .value_kind:     by_value
      - .offset:         216
        .size:           4
        .value_kind:     hidden_block_count_x
      - .offset:         220
        .size:           4
        .value_kind:     hidden_block_count_y
      - .offset:         224
        .size:           4
        .value_kind:     hidden_block_count_z
      - .offset:         228
        .size:           2
        .value_kind:     hidden_group_size_x
      - .offset:         230
        .size:           2
        .value_kind:     hidden_group_size_y
      - .offset:         232
        .size:           2
        .value_kind:     hidden_group_size_z
      - .offset:         234
        .size:           2
        .value_kind:     hidden_remainder_x
      - .offset:         236
        .size:           2
        .value_kind:     hidden_remainder_y
      - .offset:         238
        .size:           2
        .value_kind:     hidden_remainder_z
      - .offset:         256
        .size:           8
        .value_kind:     hidden_global_offset_x
      - .offset:         264
        .size:           8
        .value_kind:     hidden_global_offset_y
      - .offset:         272
        .size:           8
        .value_kind:     hidden_global_offset_z
      - .offset:         280
        .size:           2
        .value_kind:     hidden_grid_dims
      - .offset:         304
        .size:           8
        .value_kind:     hidden_multigrid_sync_arg
      - .offset:         336
        .size:           4
        .value_kind:     hidden_dynamic_lds_size
    .group_segment_fixed_size: 0
    .kernarg_segment_align: 8
    .kernarg_segment_size: 472
    .language:       OpenCL C
    .language_version:
      - 2
      - 0
    .max_flat_workgroup_size: 512
    .name:           _Z4mega6Paramsii
    .private_segment_fixed_size: 0
    .sgpr_count:     108
    .sgpr_spill_count: 135
    .symbol:         _Z4mega6Paramsii.kd
    .uniform_work_group_size: 1
    .uses_dynamic_stack: false
    .vgpr_count:     256
    .vgpr_spill_count: 0
    .wavefront_size: 64
